# S5 final pass: D-vector load hoisted to the item start
# baseline (speedup 1.0000x reference)
.LBB0_275:
	s_or_b64 exec, exec, s[4:5]
	s_waitcnt lgkmcnt(0)
	v_mfma_f32_16x16x32_bf16 v[42:45], v[72:75], v[42:45], 0
	v_mul_f32_e32 v63, v33, v62
	v_fma_f32 v63, v32, v0, -v63
	v_mul_f32_e32 v0, v33, v0
	v_mfma_f32_16x16x32_bf16 v[68:71], v[72:75], v[68:71], 0
	s_nop 7
	ds_write2_b32 v80, v42, v68 offset1:16
	ds_write2_b32 v80, v43, v69 offset0:132 offset1:148
	ds_write2_b32 v82, v44, v70 offset0:8 offset1:24
	v_mfma_f32_16x16x32_bf16 v[64:67], v[72:75], v[64:67], 0
	v_fmac_f32_e32 v0, v32, v62
	v_readlane_b32 s4, v245, 53
	v_mfma_f32_16x16x32_bf16 v[50:53], v[72:75], v[50:53], 0
	ds_write2_b32 v82, v45, v71 offset0:140 offset1:156
	s_nop 6
	ds_write2_b32 v80, v64, v50 offset0:32 offset1:48
	ds_write2_b32 v80, v65, v51 offset0:164 offset1:180
	v_mfma_f32_16x16x32_bf16 v[54:57], v[72:75], v[54:57], 0
	v_mfma_f32_16x16x32_bf16 v[42:45], v[72:75], v[46:49], 0
	ds_write2_b32 v82, v66, v52 offset0:40 offset1:56
	ds_write2_b32 v82, v67, v53 offset0:172 offset1:188
	s_nop 5
	ds_write2_b32 v80, v54, v42 offset0:64 offset1:80
	ds_write2_b32 v80, v55, v43 offset0:196 offset1:212
	ds_write2_b32 v82, v56, v44 offset0:72 offset1:88
	ds_write2_b32 v82, v57, v45 offset0:204 offset1:220
	v_mfma_f32_16x16x32_bf16 v[38:41], v[72:75], v[38:41], 0
	v_mfma_f32_16x16x32_bf16 v[34:37], v[72:75], v[34:37], 0
	s_nop 7
	ds_write2_b32 v80, v38, v34 offset0:96 offset1:112
	ds_write2_b32 v80, v39, v35 offset0:228 offset1:244
	ds_write2_b32 v82, v40, v36 offset0:104 offset1:120
	ds_write2_b32 v82, v41, v37 offset0:236 offset1:252
	s_waitcnt lgkmcnt(0)
	ds_read2st64_b32 v[10:11], v84 offset0:42 offset1:43
	ds_read2st64_b32 v[34:35], v85 offset0:40 offset1:41
	ds_read2st64_b32 v[36:37], v86 offset0:38 offset1:39
	ds_read2st64_b32 v[38:39], v87 offset0:36 offset1:37
	ds_read2st64_b32 v[40:41], v88 offset0:34 offset1:35
	ds_read2st64_b32 v[42:43], v89 offset0:32 offset1:33
	ds_read2st64_b32 v[44:45], v90 offset0:30 offset1:31
	ds_read2st64_b32 v[46:47], v91 offset0:28 offset1:29
	ds_read2st64_b32 v[48:49], v92 offset0:26 offset1:27
	ds_read2st64_b32 v[50:51], v93 offset0:24 offset1:25
	ds_read2st64_b32 v[52:53], v94 offset0:22 offset1:23
	ds_read2st64_b32 v[54:55], v95 offset0:20 offset1:21
	ds_read2st64_b32 v[56:57], v96 offset0:18 offset1:19
	ds_read2st64_b32 v[64:65], v97 offset0:16 offset1:17
	ds_read2st64_b32 v[66:67], v98 offset0:14 offset1:15
	ds_read2st64_b32 v[68:69], v83 offset0:12 offset1:13
	s_waitcnt lgkmcnt(14)
	v_add_f32_e32 v10, v63, v10
	v_add_f32_e32 v0, v0, v11
	v_cvt_pk_bf16_f32 v11, v10, v0
	v_fma_f32 v62, v33, v10, v35
	v_fma_f32 v34, v32, v10, v34
	v_fma_f32 v34, -v33, v0, v34
	v_fma_f32 v0, v32, v0, v62
	v_cvt_pk_bf16_f32 v10, v34, v0
	ds_write2_b32 v99, v10, v11 offset0:120 offset1:188
	s_waitcnt lgkmcnt(14)
	v_fma_f32 v11, v33, v34, v37
	v_fma_f32 v10, v32, v34, v36
	v_fma_f32 v10, -v33, v0, v10
	v_fma_f32 v0, v32, v0, v11
	v_cvt_pk_bf16_f32 v11, v10, v0
	s_waitcnt lgkmcnt(13)
	v_fma_f32 v34, -v0, v33, v38
	v_fma_f32 v0, v0, v32, v39
	v_fma_f32 v0, v10, v33, v0
	v_fma_f32 v34, v10, v32, v34
	v_cvt_pk_bf16_f32 v10, v34, v0
	ds_write2_b32 v100, v10, v11 offset0:112 offset1:180
	s_waitcnt lgkmcnt(13)
	v_fma_f32 v11, v33, v34, v41
	v_fma_f32 v10, v32, v34, v40
	v_fma_f32 v10, -v33, v0, v10
	v_fma_f32 v0, v32, v0, v11
	v_cvt_pk_bf16_f32 v11, v10, v0
	s_waitcnt lgkmcnt(12)
	v_fma_f32 v34, -v0, v33, v42
	v_fma_f32 v0, v0, v32, v43
	v_fma_f32 v0, v10, v33, v0
	v_fma_f32 v34, v10, v32, v34
	v_cvt_pk_bf16_f32 v10, v34, v0
	ds_write2_b32 v101, v10, v11 offset0:104 offset1:172
	s_waitcnt lgkmcnt(12)
	v_fma_f32 v11, v33, v34, v45
	v_fma_f32 v10, v32, v34, v44
	v_fma_f32 v10, -v33, v0, v10
	v_fma_f32 v0, v32, v0, v11
	v_cvt_pk_bf16_f32 v11, v10, v0
	s_waitcnt lgkmcnt(11)
	v_fma_f32 v34, -v0, v33, v46
	v_fma_f32 v0, v0, v32, v47
	v_fma_f32 v0, v10, v33, v0
	v_fma_f32 v34, v10, v32, v34
	v_cvt_pk_bf16_f32 v10, v34, v0
	ds_write2_b32 v102, v10, v11 offset0:96 offset1:164
	s_waitcnt lgkmcnt(11)
	v_fma_f32 v11, v33, v34, v49
	v_fma_f32 v10, v32, v34, v48
	v_fma_f32 v10, -v33, v0, v10
	v_fma_f32 v0, v32, v0, v11
	v_cvt_pk_bf16_f32 v11, v10, v0
	s_waitcnt lgkmcnt(10)
	v_fma_f32 v34, -v0, v33, v50
	v_fma_f32 v0, v0, v32, v51
	v_fma_f32 v0, v10, v33, v0
	v_fma_f32 v34, v10, v32, v34
	v_cvt_pk_bf16_f32 v10, v34, v0
	ds_write2_b32 v103, v10, v11 offset0:88 offset1:156
	s_waitcnt lgkmcnt(10)
	v_fma_f32 v11, v33, v34, v53
	v_fma_f32 v10, v32, v34, v52
	v_fma_f32 v10, -v33, v0, v10
	v_fma_f32 v0, v32, v0, v11
	v_cvt_pk_bf16_f32 v11, v10, v0
	s_waitcnt lgkmcnt(9)
	v_fma_f32 v34, -v0, v33, v54
	v_fma_f32 v0, v0, v32, v55
	v_fma_f32 v0, v10, v33, v0
	v_fma_f32 v34, v10, v32, v34
	v_cvt_pk_bf16_f32 v10, v34, v0
	ds_write2_b32 v104, v10, v11 offset0:80 offset1:148
	s_waitcnt lgkmcnt(9)
	v_fma_f32 v11, v33, v34, v57
	v_fma_f32 v10, v32, v34, v56
	v_fma_f32 v10, -v33, v0, v10
	v_fma_f32 v0, v32, v0, v11
	v_cvt_pk_bf16_f32 v11, v10, v0
	s_waitcnt lgkmcnt(8)
	v_fma_f32 v34, -v0, v33, v64
	v_fma_f32 v0, v0, v32, v65
	v_fma_f32 v0, v10, v33, v0
	v_fma_f32 v34, v10, v32, v34
	v_cvt_pk_bf16_f32 v10, v34, v0
	ds_write2_b32 v105, v10, v11 offset0:72 offset1:140
	s_waitcnt lgkmcnt(8)
	v_fma_f32 v11, v33, v34, v67
	v_fma_f32 v10, v32, v34, v66
	v_fma_f32 v10, -v33, v0, v10
	v_fma_f32 v0, v32, v0, v11
	v_cvt_pk_bf16_f32 v11, v10, v0
	s_waitcnt lgkmcnt(7)
	v_fma_f32 v34, -v0, v33, v68
	v_fma_f32 v0, v0, v32, v69
	v_fma_f32 v0, v10, v33, v0
	v_fma_f32 v34, v10, v32, v34
	v_cvt_pk_bf16_f32 v0, v34, v0
	ds_write2_b32 v106, v0, v11 offset0:64 offset1:132
	s_waitcnt lgkmcnt(0)
	v_mov_b32_e32 v0, s4
	ds_read_b64 v[10:11], v0
	s_lshr_b32 s4, s23, 6
	v_lshrrev_b32_e32 v0, 2, v78
	v_and_b32_e32 v46, 15, v78
	s_mulk_i32 s4, 0x3e00
	v_and_b32_e32 v47, 12, v0
	ds_read_b128 v[32:35], v79 offset:11520
	ds_read_b128 v[36:39], v79 offset:11584
	s_add_i32 s4, s4, 0
	v_lshlrev_b32_e32 v0, 1, v46
	v_mul_u32_u24_e32 v41, 48, v47
	v_add3_u32 v48, s4, v0, v41
	s_waitcnt lgkmcnt(2)
	v_readfirstlane_b32 s4, v11
	v_readfirstlane_b32 s5, v10
	s_waitcnt lgkmcnt(1)
	v_mfma_f32_16x16x32_bf16 v[2:5], v[32:35], v[20:23], v[2:5]
	v_mov_b32_e32 v11, s4
	v_mov_b32_e32 v10, s5
	v_readlane_b32 s4, v245, 4
	s_add_i32 s4, s0, s4
	v_mov_b32_e32 v40, s59
	v_or_b32_e32 v20, s4, v46
	v_ashrrev_i32_e32 v21, 31, v20
	v_lshl_add_u64 v[10:11], v[20:21], 2, v[10:11]
	ds_read_u16 v49, v48
	ds_read_b64 v[44:45], v40
	v_mov_b32_e32 v10, v231
	ds_read_b128 v[40:43], v79 offset:11648
	ds_read_b128 v[20:23], v79 offset:11712
	s_waitcnt lgkmcnt(0)
	v_mfma_f32_16x16x32_bf16 v[2:5], v[36:39], v[28:31], v[2:5]
	v_readlane_b32 s5, v245, 5
	v_readfirstlane_b32 s5, v44
	s_lshl_b64 s[0:1], s[0:1], 1
	v_mfma_f32_16x16x32_bf16 v[2:5], v[40:43], v[24:27], v[2:5]
	v_readfirstlane_b32 s4, v45
	s_add_u32 s0, s5, s0
	s_addc_u32 s1, s4, s1
	v_mfma_f32_16x16x32_bf16 v[16:19], v[20:23], v[16:19], v[2:5]
	s_lshl_b32 s4, s22, 6
	s_add_i32 s10, s10, s54
	s_add_i32 s17, s17, s60
	s_nop 0
	v_lshl_add_u64 v[2:3], s[0:1], 0, v[0:1]
	v_lshlrev_b32_e32 v0, 16, v49
	s_mov_b64 s[0:1], 0xcc00000
	v_lshl_add_u64 v[2:3], v[2:3], 0, s[0:1]
	s_lshl_b32 s0, s20, 12
	s_lshl_b32 s1, s20, 8
	s_add_i32 s0, s22, s0
	s_add_i32 s1, s1, s4
	s_add_i32 s0, s0, -4
	s_add_i32 s1, s1, 0x8000
	v_lshl_add_u32 v5, v47, 6, s0
	s_waitcnt vmcnt(0)
	v_fma_f32 v0, v10, v0, v16
	v_mul_f32_e32 v4, v0, v0
	v_fmamk_f32 v4, v4, 0xbdd2d3e8, v211
	v_mul_f32_e32 v4, v0, v4
	v_exp_f32_e32 v4, v4
	s_nop 0
	v_add_f32_e32 v4, 1.0, v4
	v_rcp_f32_e32 v4, v4
	s_nop 0
	v_mul_f32_e32 v0, v0, v4
	v_or_b32_e32 v4, s1, v47
	v_cndmask_b32_e64 v4, v5, v4, s[36:37]
	v_ashrrev_i32_e32 v5, 31, v4
	v_lshlrev_b64 v[4:5], 9, v[4:5]
	v_cvt_pk_bf16_f32 v0, v0, s0
	v_lshl_add_u64 v[4:5], v[2:3], 0, v[4:5]
	global_store_short v[4:5], v0, off
	ds_read_u16 v0, v48 offset:48
	v_or_b32_e32 v5, 1, v47
	s_waitcnt lgkmcnt(0)
	v_lshlrev_b32_e32 v0, 16, v0
	v_fma_f32 v0, v10, v0, v17
	v_mul_f32_e32 v4, v0, v0
	v_fmamk_f32 v4, v4, 0xbdd2d3e8, v211
	v_mul_f32_e32 v4, v0, v4
	v_exp_f32_e32 v4, v4
	s_nop 0
	v_add_f32_e32 v4, 1.0, v4
	v_rcp_f32_e32 v4, v4
	s_nop 0
	v_mul_f32_e32 v0, v0, v4
	v_or_b32_e32 v4, s1, v5
	v_lshl_add_u32 v5, v5, 6, s0
	v_cndmask_b32_e64 v4, v5, v4, s[36:37]
	v_ashrrev_i32_e32 v5, 31, v4
	v_lshlrev_b64 v[4:5], 9, v[4:5]
	v_cvt_pk_bf16_f32 v0, v0, s0
	v_lshl_add_u64 v[4:5], v[2:3], 0, v[4:5]
	global_store_short v[4:5], v0, off
	ds_read_u16 v0, v48 offset:96
	v_or_b32_e32 v5, 2, v47
	s_waitcnt lgkmcnt(0)
	v_lshlrev_b32_e32 v0, 16, v0
	v_fma_f32 v0, v10, v0, v18
	v_mul_f32_e32 v4, v0, v0
	v_fmamk_f32 v4, v4, 0xbdd2d3e8, v211
	v_mul_f32_e32 v4, v0, v4
	v_exp_f32_e32 v4, v4
	s_nop 0
	v_add_f32_e32 v4, 1.0, v4
	v_rcp_f32_e32 v4, v4
	s_nop 0
	v_mul_f32_e32 v0, v0, v4
	v_or_b32_e32 v4, s1, v5
	v_lshl_add_u32 v5, v5, 6, s0
	v_cndmask_b32_e64 v4, v5, v4, s[36:37]
	v_ashrrev_i32_e32 v5, 31, v4
	v_lshlrev_b64 v[4:5], 9, v[4:5]
	v_cvt_pk_bf16_f32 v0, v0, s0
	v_lshl_add_u64 v[4:5], v[2:3], 0, v[4:5]
	global_store_short v[4:5], v0, off
	ds_read_u16 v0, v48 offset:144
	v_or_b32_e32 v4, 3, v47
	v_or_b32_e32 v5, s1, v4
	v_lshl_add_u32 v4, v4, 6, s0
	v_cndmask_b32_e64 v4, v4, v5, s[36:37]
	s_waitcnt lgkmcnt(0)
	v_lshlrev_b32_e32 v0, 16, v0
	v_fmac_f32_e32 v19, v10, v0
	v_mul_f32_e32 v0, v19, v19
	v_fmamk_f32 v0, v0, 0xbdd2d3e8, v211
	v_mul_f32_e32 v0, v19, v0
	v_exp_f32_e32 v0, v0
	v_ashrrev_i32_e32 v5, 31, v4
	v_lshlrev_b64 v[4:5], 9, v[4:5]
	v_lshl_add_u64 v[4:5], v[2:3], 0, v[4:5]
	v_add_f32_e32 v0, 1.0, v0
	v_rcp_f32_e32 v0, v0
	s_nop 0
	v_mul_f32_e32 v0, v19, v0
	v_cvt_pk_bf16_f32 v0, v0, s0
	global_store_short v[4:5], v0, off
	ds_read_u16 v0, v48 offset:768
	v_or_b32_e32 v5, 16, v47
	s_waitcnt lgkmcnt(0)
	v_lshlrev_b32_e32 v0, 16, v0
	v_fma_f32 v0, v10, v0, v6
	v_mul_f32_e32 v4, v0, v0
	v_fmamk_f32 v4, v4, 0xbdd2d3e8, v211
	v_mul_f32_e32 v4, v0, v4
	v_exp_f32_e32 v4, v4
	s_nop 0
	v_add_f32_e32 v4, 1.0, v4
	v_rcp_f32_e32 v4, v4
	s_nop 0
	v_mul_f32_e32 v0, v0, v4
	v_or_b32_e32 v4, s1, v5
	v_lshl_add_u32 v5, v5, 6, s0
	v_cndmask_b32_e64 v4, v5, v4, s[36:37]
	v_ashrrev_i32_e32 v5, 31, v4
	v_lshlrev_b64 v[4:5], 9, v[4:5]
	v_cvt_pk_bf16_f32 v0, v0, s0
	v_lshl_add_u64 v[4:5], v[2:3], 0, v[4:5]
	global_store_short v[4:5], v0, off
	ds_read_u16 v0, v48 offset:816
	v_or_b32_e32 v5, 17, v47
	s_waitcnt lgkmcnt(0)
	v_lshlrev_b32_e32 v0, 16, v0
	v_fma_f32 v0, v10, v0, v7
	v_mul_f32_e32 v4, v0, v0
	v_fmamk_f32 v4, v4, 0xbdd2d3e8, v211
	v_mul_f32_e32 v4, v0, v4
	v_exp_f32_e32 v4, v4
	s_nop 0
	v_add_f32_e32 v4, 1.0, v4
	v_rcp_f32_e32 v4, v4
	s_nop 0
	v_mul_f32_e32 v0, v0, v4
	v_or_b32_e32 v4, s1, v5
	v_lshl_add_u32 v5, v5, 6, s0
	v_cndmask_b32_e64 v4, v5, v4, s[36:37]
	v_ashrrev_i32_e32 v5, 31, v4
	v_lshlrev_b64 v[4:5], 9, v[4:5]
	v_cvt_pk_bf16_f32 v0, v0, s0
	v_lshl_add_u64 v[4:5], v[2:3], 0, v[4:5]
	global_store_short v[4:5], v0, off
	ds_read_u16 v0, v48 offset:864
	v_or_b32_e32 v5, 18, v47
	s_waitcnt lgkmcnt(0)
	v_lshlrev_b32_e32 v0, 16, v0
	v_fma_f32 v0, v10, v0, v8
	v_mul_f32_e32 v4, v0, v0
	v_fmamk_f32 v4, v4, 0xbdd2d3e8, v211
	v_mul_f32_e32 v4, v0, v4
	v_exp_f32_e32 v4, v4
	s_nop 0
	v_add_f32_e32 v4, 1.0, v4
	v_rcp_f32_e32 v4, v4
	s_nop 0
	v_mul_f32_e32 v0, v0, v4
	v_or_b32_e32 v4, s1, v5
	v_lshl_add_u32 v5, v5, 6, s0
	v_cndmask_b32_e64 v4, v5, v4, s[36:37]
	v_ashrrev_i32_e32 v5, 31, v4
	v_lshlrev_b64 v[4:5], 9, v[4:5]
	v_cvt_pk_bf16_f32 v0, v0, s0
	v_lshl_add_u64 v[4:5], v[2:3], 0, v[4:5]
	global_store_short v[4:5], v0, off
	ds_read_u16 v0, v48 offset:912
	v_or_b32_e32 v4, 19, v47
	v_or_b32_e32 v5, s1, v4
	v_lshl_add_u32 v4, v4, 6, s0
	v_cndmask_b32_e64 v4, v4, v5, s[36:37]
	s_waitcnt lgkmcnt(0)
	v_lshlrev_b32_e32 v0, 16, v0
	v_fmac_f32_e32 v9, v10, v0
	v_mul_f32_e32 v0, v9, v9
	v_fmamk_f32 v0, v0, 0xbdd2d3e8, v211
	v_mul_f32_e32 v0, v9, v0
	v_exp_f32_e32 v0, v0
	v_ashrrev_i32_e32 v5, 31, v4
	v_lshlrev_b64 v[4:5], 9, v[4:5]
	v_lshl_add_u64 v[4:5], v[2:3], 0, v[4:5]
	v_add_f32_e32 v0, 1.0, v0
	v_rcp_f32_e32 v0, v0
	s_nop 0
	v_mul_f32_e32 v0, v9, v0
	v_cvt_pk_bf16_f32 v0, v0, s0
	global_store_short v[4:5], v0, off
	ds_read_u16 v0, v48 offset:1536
	v_or_b32_e32 v5, 32, v47
	s_waitcnt lgkmcnt(0)
	v_lshlrev_b32_e32 v0, 16, v0
	v_fma_f32 v0, v10, v0, v58
	v_mul_f32_e32 v4, v0, v0
	v_fmamk_f32 v4, v4, 0xbdd2d3e8, v211
	v_mul_f32_e32 v4, v0, v4
	v_exp_f32_e32 v4, v4
	s_nop 0
	v_add_f32_e32 v4, 1.0, v4
	v_rcp_f32_e32 v4, v4
	s_nop 0
	v_mul_f32_e32 v0, v0, v4
	v_or_b32_e32 v4, s1, v5
	v_lshl_add_u32 v5, v5, 6, s0
	v_cndmask_b32_e64 v4, v5, v4, s[36:37]
	v_ashrrev_i32_e32 v5, 31, v4
	v_lshlrev_b64 v[4:5], 9, v[4:5]
	v_cvt_pk_bf16_f32 v0, v0, s0
	v_lshl_add_u64 v[4:5], v[2:3], 0, v[4:5]
	global_store_short v[4:5], v0, off
	ds_read_u16 v0, v48 offset:1584
	v_or_b32_e32 v5, 33, v47
	s_waitcnt lgkmcnt(0)
	v_lshlrev_b32_e32 v0, 16, v0
	v_fma_f32 v0, v10, v0, v59
	v_mul_f32_e32 v4, v0, v0
	v_fmamk_f32 v4, v4, 0xbdd2d3e8, v211
	v_mul_f32_e32 v4, v0, v4
	v_exp_f32_e32 v4, v4
	s_nop 0
	v_add_f32_e32 v4, 1.0, v4
	v_rcp_f32_e32 v4, v4
	s_nop 0
	v_mul_f32_e32 v0, v0, v4
	v_or_b32_e32 v4, s1, v5
	v_lshl_add_u32 v5, v5, 6, s0
	v_cndmask_b32_e64 v4, v5, v4, s[36:37]
	v_ashrrev_i32_e32 v5, 31, v4
	v_lshlrev_b64 v[4:5], 9, v[4:5]
	v_cvt_pk_bf16_f32 v0, v0, s0
	v_lshl_add_u64 v[4:5], v[2:3], 0, v[4:5]
	global_store_short v[4:5], v0, off
	ds_read_u16 v0, v48 offset:1632
	v_or_b32_e32 v5, 34, v47
	s_waitcnt lgkmcnt(0)
	v_lshlrev_b32_e32 v0, 16, v0
	v_fma_f32 v0, v10, v0, v60
	v_mul_f32_e32 v4, v0, v0
	v_fmamk_f32 v4, v4, 0xbdd2d3e8, v211
	v_mul_f32_e32 v4, v0, v4
	v_exp_f32_e32 v4, v4
	s_nop 0
	v_add_f32_e32 v4, 1.0, v4
	v_rcp_f32_e32 v4, v4
	s_nop 0
	v_mul_f32_e32 v0, v0, v4
	v_or_b32_e32 v4, s1, v5
	v_lshl_add_u32 v5, v5, 6, s0
	v_cndmask_b32_e64 v4, v5, v4, s[36:37]
	v_ashrrev_i32_e32 v5, 31, v4
	v_lshlrev_b64 v[4:5], 9, v[4:5]
	v_cvt_pk_bf16_f32 v0, v0, s0
	v_lshl_add_u64 v[4:5], v[2:3], 0, v[4:5]
	global_store_short v[4:5], v0, off
	ds_read_u16 v0, v48 offset:1680
	v_or_b32_e32 v4, 35, v47
	v_or_b32_e32 v5, s1, v4
	v_lshl_add_u32 v4, v4, 6, s0
	v_cndmask_b32_e64 v4, v4, v5, s[36:37]
	s_waitcnt lgkmcnt(0)
	v_lshlrev_b32_e32 v0, 16, v0
	v_fmac_f32_e32 v61, v10, v0
	v_mul_f32_e32 v0, v61, v61
	v_fmamk_f32 v0, v0, 0xbdd2d3e8, v211
	v_mul_f32_e32 v0, v61, v0
	v_exp_f32_e32 v0, v0
	v_ashrrev_i32_e32 v5, 31, v4
	v_lshlrev_b64 v[4:5], 9, v[4:5]
	v_lshl_add_u64 v[4:5], v[2:3], 0, v[4:5]
	v_add_f32_e32 v0, 1.0, v0
	v_rcp_f32_e32 v0, v0
	s_nop 0
	v_mul_f32_e32 v0, v61, v0
	v_cvt_pk_bf16_f32 v0, v0, s0
	global_store_short v[4:5], v0, off
	ds_read_u16 v0, v48 offset:2304
	v_or_b32_e32 v5, 48, v47
	s_waitcnt lgkmcnt(0)
	v_lshlrev_b32_e32 v0, 16, v0
	v_fma_f32 v0, v10, v0, v12
	v_mul_f32_e32 v4, v0, v0
	v_fmamk_f32 v4, v4, 0xbdd2d3e8, v211
	v_mul_f32_e32 v4, v0, v4
	v_exp_f32_e32 v4, v4
	s_nop 0
	v_add_f32_e32 v4, 1.0, v4
	v_rcp_f32_e32 v4, v4
	s_nop 0
	v_mul_f32_e32 v0, v0, v4
	v_or_b32_e32 v4, s1, v5
	v_lshl_add_u32 v5, v5, 6, s0
	v_cndmask_b32_e64 v4, v5, v4, s[36:37]
	v_ashrrev_i32_e32 v5, 31, v4
	v_lshlrev_b64 v[4:5], 9, v[4:5]
	v_cvt_pk_bf16_f32 v0, v0, s0
	v_lshl_add_u64 v[4:5], v[2:3], 0, v[4:5]
	global_store_short v[4:5], v0, off
	ds_read_u16 v0, v48 offset:2352
	v_or_b32_e32 v5, 49, v47
	s_waitcnt lgkmcnt(0)
	v_lshlrev_b32_e32 v0, 16, v0
	v_fma_f32 v0, v10, v0, v13
	v_mul_f32_e32 v4, v0, v0
	v_fmamk_f32 v4, v4, 0xbdd2d3e8, v211
	v_mul_f32_e32 v4, v0, v4
	v_exp_f32_e32 v4, v4
	s_nop 0
	v_add_f32_e32 v4, 1.0, v4
	v_rcp_f32_e32 v4, v4
	s_nop 0
	v_mul_f32_e32 v0, v0, v4
	v_or_b32_e32 v4, s1, v5
	v_lshl_add_u32 v5, v5, 6, s0
	v_cndmask_b32_e64 v4, v5, v4, s[36:37]
	v_ashrrev_i32_e32 v5, 31, v4
	v_lshlrev_b64 v[4:5], 9, v[4:5]
	v_cvt_pk_bf16_f32 v0, v0, s0
	v_lshl_add_u64 v[4:5], v[2:3], 0, v[4:5]
	global_store_short v[4:5], v0, off
	ds_read_u16 v0, v48 offset:2400
	v_or_b32_e32 v5, 50, v47
	s_waitcnt lgkmcnt(0)
	v_lshlrev_b32_e32 v0, 16, v0
	v_fma_f32 v0, v10, v0, v14
	v_mul_f32_e32 v4, v0, v0
	v_fmamk_f32 v4, v4, 0xbdd2d3e8, v211
	v_mul_f32_e32 v4, v0, v4
	v_exp_f32_e32 v4, v4
	s_nop 0
	v_add_f32_e32 v4, 1.0, v4
	v_rcp_f32_e32 v4, v4
	s_nop 0
	v_mul_f32_e32 v0, v0, v4
	v_or_b32_e32 v4, s1, v5
	v_lshl_add_u32 v5, v5, 6, s0
	v_cndmask_b32_e64 v4, v5, v4, s[36:37]
	v_ashrrev_i32_e32 v5, 31, v4
	v_lshlrev_b64 v[4:5], 9, v[4:5]
	v_cvt_pk_bf16_f32 v0, v0, s0
	v_lshl_add_u64 v[4:5], v[2:3], 0, v[4:5]
	global_store_short v[4:5], v0, off
	ds_read_u16 v0, v48 offset:2448
	v_or_b32_e32 v4, 51, v47
	v_or_b32_e32 v5, s1, v4
	v_lshl_add_u32 v4, v4, 6, s0
	v_cndmask_b32_e64 v4, v4, v5, s[36:37]
	s_waitcnt lgkmcnt(0)
	v_lshlrev_b32_e32 v0, 16, v0
	v_fmac_f32_e32 v15, v10, v0
	v_mul_f32_e32 v0, v15, v15
	v_fmamk_f32 v0, v0, 0xbdd2d3e8, v211
	v_mul_f32_e32 v0, v15, v0
	v_exp_f32_e32 v0, v0
	v_ashrrev_i32_e32 v5, 31, v4
	v_lshlrev_b64 v[4:5], 9, v[4:5]
	v_lshl_add_u64 v[2:3], v[2:3], 0, v[4:5]
	v_add_f32_e32 v0, 1.0, v0
	v_rcp_f32_e32 v0, v0
	s_nop 0
	v_mul_f32_e32 v0, v15, v0
	v_cvt_pk_bf16_f32 v0, v0, s0
	global_store_short v[2:3], v0, off
	s_waitcnt lgkmcnt(0)
	v_readlane_b32 s0, v244, 24
	s_cmp_lt_i32 s10, s0
	s_cbranch_scc0 .LBB0_296

.LBB0_280:
	s_and_b32 s4, s17, 8
	v_mov_b64_e32 v[4:5], s[0:1]
	s_add_i32 s4, s4, s11
	v_mad_i64_i32 v[2:3], s[0:1], v2, s94, v[4:5]
	s_lshl_b32 s0, s4, 4
	s_ashr_i32 s1, s0, 31
	s_lshr_b32 s5, s6, 6
	v_lshl_add_u64 v[2:3], s[0:1], 1, v[2:3]
	s_mov_b64 s[6:7], 0xe001000
	v_lshl_add_u64 v[6:7], v[2:3], 0, s[6:7]
	v_add_co_u32_e32 v2, vcc, 0xe001000, v2
	s_mulk_i32 s5, 0x3e00
	s_nop 0
	v_addc_co_u32_e32 v3, vcc, 0, v3, vcc
	global_load_dwordx4 v[222:225], v[2:3], off
	s_nop 0
	global_load_dwordx4 v[226:229], v[6:7], off offset:16
	s_add_i32 s5, s5, 0
	v_mad_u32_u24 v0, v0, 48, s5
	v_mov_b32_e32 v62, v204
	s_add_i32 s6, s4, s21
	s_ashr_i32 s7, s6, 31
	s_lshl_b64 s[26:27], s[6:7], 13
	v_mov_b32_e32 v230, v0
	v_readlane_b32 s5, v245, 4
	v_mov_b32_e32 v231, 0x230d0
	ds_read_b64 v[232:233], v231
	v_and_b32_e32 v231, 15, v204
	s_add_i32 s5, s0, s5
	v_mov_b32_e32 v235, 0
	v_or_b32_e32 v234, s5, v231
	s_waitcnt lgkmcnt(0)
	v_lshl_add_u64 v[232:233], v[234:235], 2, v[232:233]
	global_load_dword v231, v[232:233], off
	v_mov_b32_e32 v0, s59
	s_waitcnt lgkmcnt(0)
	ds_read_b64 v[2:3], v0
	v_and_b32_e32 v61, 63, v62
	v_readfirstlane_b32 s5, v62
	s_lshr_b32 s5, s5, 6
	s_mulk_i32 s5, 0x3e00
	s_waitcnt lgkmcnt(0)
	v_readfirstlane_b32 s8, v2
	v_lshl_or_b32 v2, s6, 6, v61
	v_readfirstlane_b32 s9, v3
	v_ashrrev_i32_e32 v3, 31, v2
	s_add_i32 s28, s5, 0
	v_lshl_add_u64 v[2:3], v[2:3], 4, s[8:9]
	s_mov_b32 s5, 0x200000
	v_add_co_u32_e32 v2, vcc, s5, v2
	s_add_u32 s26, s8, s26
	v_and_b32_e32 v60, 15, v62
	v_addc_co_u32_e32 v3, vcc, 0, v3, vcc
	s_addc_u32 s27, s9, s27
	v_and_b32_e32 v0, 48, v62
	global_load_dwordx2 v[6:7], v[2:3], off
	v_lshl_add_u64 v[2:3], s[26:27], 0, v[0:1]
	v_lshlrev_b32_e32 v4, 6, v60
	v_mov_b32_e32 v5, v1
	v_lshl_add_u64 v[2:3], v[2:3], 0, v[4:5]
	s_mov_b32 s5, 0x240000
	s_waitcnt lgkmcnt(0)
	v_add_co_u32_e32 v8, vcc, s5, v2
	s_mov_b64 s[26:27], 0x240000
	s_nop 0
	v_addc_co_u32_e32 v9, vcc, 0, v3, vcc
	s_mov_b32 s5, 0x241000
	v_lshl_add_u64 v[4:5], v[2:3], 0, s[26:27]
	v_add_co_u32_e32 v2, vcc, s5, v2
	s_lshl_b64 s[6:7], s[6:7], 12
	s_nop 0
	v_addc_co_u32_e32 v3, vcc, 0, v3, vcc
	s_add_u32 s6, s8, s6
	global_load_dwordx4 v[52:55], v[8:9], off
	global_load_dwordx4 v[56:59], v[4:5], off offset:1024
	global_load_dwordx4 v[44:47], v[4:5], off offset:2048
	global_load_dwordx4 v[48:51], v[4:5], off offset:3072
	global_load_dwordx4 v[40:43], v[2:3], off
	global_load_dwordx4 v[36:39], v[2:3], off offset:1024
	global_load_dwordx4 v[32:35], v[2:3], off offset:2048
	global_load_dwordx4 v[28:31], v[2:3], off offset:3072
	s_addc_u32 s7, s9, s7
	v_lshlrev_b32_e32 v2, 8, v60
	v_mov_b32_e32 v3, v1
	v_lshl_add_u64 v[2:3], s[6:7], 0, v[2:3]
	v_lshl_add_u64 v[2:3], v[2:3], 0, v[0:1]
	s_mov_b64 s[6:7], 0x380000
	v_lshl_add_u64 v[4:5], v[2:3], 0, s[6:7]
	s_mov_b32 s5, 0x380000
	s_lshl_b32 s26, s20, 1
	s_mul_i32 s6, s20, 0x88
	s_ashr_i32 s27, s22, 31
	v_add_co_u32_e32 v2, vcc, s5, v2
	s_mul_hi_i32 s5, s26, 0x44
	s_add_u32 s6, s6, s22
	s_addc_u32 s7, s5, s27
	s_ashr_i32 s5, s4, 31
	s_lshl_b64 s[38:39], s[6:7], 10
	s_lshl_b64 s[6:7], s[4:5], 6
	s_add_u32 s5, s38, s6
	v_addc_co_u32_e32 v3, vcc, 0, v3, vcc
	s_addc_u32 s29, s39, s7
	global_load_dwordx4 v[24:27], v[2:3], off
	global_load_dwordx4 v[20:23], v[4:5], off offset:64
	global_load_dwordx4 v[16:19], v[4:5], off offset:128
	global_load_dwordx4 v[12:15], v[4:5], off offset:192
	v_or_b32_e32 v2, s5, v61
	v_mov_b32_e32 v3, s29
	v_lshl_add_u64 v[2:3], v[2:3], 3, s[8:9]
	v_add_co_u32_e32 v2, vcc, 0x1500000, v2
	v_mov_b32_e32 v8, 0
	s_nop 0
	v_addc_co_u32_e32 v3, vcc, 0, v3, vcc
	global_load_dwordx2 v[10:11], v[2:3], off
	v_add_u32_e32 v2, s28, v0
	v_cmp_gt_u32_e32 vcc, 32, v61
	v_mad_u32_u24 v95, v60, 48, v2
	v_mov_b32_e32 v2, 0
	v_mov_b32_e32 v3, 0
	v_mov_b32_e32 v4, 0
	v_mov_b32_e32 v5, 0
	s_waitcnt vmcnt(15)
	ds_write_b128 v230, v[222:225]
	ds_write_b128 v230, v[226:229] offset:16
	s_and_saveexec_b64 s[8:9], vcc
	ds_read_b128 v[2:5], v95
	s_or_b64 exec, exec, s[8:9]
	s_waitcnt vmcnt(0) lgkmcnt(0)
	v_mfma_f32_16x16x32_bf16 v[64:67], v[2:5], v[52:55], 0
	v_bfe_u32 v9, v62, 4, 2
	v_lshlrev_b32_e32 v79, 2, v61
	v_mov_b32_e32 v61, s28
	v_mfma_f32_16x16x32_bf16 v[70:73], v[2:5], v[56:59], 0
	s_movk_i32 s5, 0x110
	v_lshlrev_b32_e32 v68, 2, v60
	v_mad_u32_u24 v112, v60, s5, v61
	v_mul_u32_u24_e32 v9, 0x840, v9
	v_mfma_f32_16x16x32_bf16 v[60:63], v[2:5], v[44:47], 0
	v_add3_u32 v9, s28, v68, v9
	v_add_u32_e32 v68, 0xc00, v9
	v_add_u32_e32 v69, 0x1000, v9
	v_mfma_f32_16x16x32_bf16 v[74:77], v[2:5], v[48:51], 0
	ds_write2_b32 v68, v64, v70 offset1:16
	ds_write2_b32 v68, v65, v71 offset0:132 offset1:148
	ds_write2_b32 v69, v66, v72 offset0:8 offset1:24
	v_mfma_f32_16x16x32_bf16 v[80:83], v[2:5], v[40:43], 0
	ds_write2_b32 v69, v67, v73 offset0:140 offset1:156
	s_nop 2
	ds_write2_b32 v68, v60, v74 offset0:32 offset1:48
	ds_write2_b32 v68, v61, v75 offset0:164 offset1:180
	v_add_u32_e32 v70, s28, v79
	v_mul_f32_e32 v9, v7, v11
	v_mfma_f32_16x16x32_bf16 v[64:67], v[2:5], v[36:39], 0
	ds_write2_b32 v69, v62, v76 offset0:40 offset1:56
	ds_write2_b32 v69, v63, v77 offset0:172 offset1:188
	s_nop 5
	ds_write2_b32 v68, v80, v64 offset0:64 offset1:80
	ds_write2_b32 v68, v81, v65 offset0:196 offset1:212
	ds_write2_b32 v69, v82, v66 offset0:72 offset1:88
	ds_write2_b32 v69, v83, v67 offset0:204 offset1:220
	v_mfma_f32_16x16x32_bf16 v[60:63], v[2:5], v[32:35], 0
	v_add_u32_e32 v71, 16, v70
	v_fma_f32 v9, v6, v10, -v9
	v_add_u32_e32 v72, 32, v70
	v_mfma_f32_16x16x32_bf16 v[2:5], v[2:5], v[28:31], 0
	s_nop 7
	ds_write2_b32 v68, v60, v2 offset0:96 offset1:112
	ds_write2_b32 v68, v61, v3 offset0:228 offset1:244
	ds_write2_b32 v69, v62, v4 offset0:104 offset1:120
	ds_write2_b32 v69, v63, v5 offset0:236 offset1:252
	s_waitcnt lgkmcnt(0)
	ds_read2st64_b32 v[2:3], v70 offset0:12 offset1:13
	ds_read2st64_b32 v[4:5], v71 offset0:14 offset1:15
	ds_read2st64_b32 v[60:61], v72 offset0:16 offset1:17
	v_add_u32_e32 v87, 0x2c00, v70
	v_add_u32_e32 v73, 48, v70
	s_waitcnt lgkmcnt(2)
	v_add_f32_e32 v2, v9, v2
	v_mul_f32_e32 v9, v7, v10
	v_fmac_f32_e32 v9, v6, v11
	v_add_f32_e32 v3, v9, v3
	v_cvt_pk_bf16_f32 v9, v2, v3
	s_waitcnt lgkmcnt(1)
	v_fma_f32 v10, v7, v2, v5
	v_fma_f32 v4, v6, v2, v4
	v_fma_f32 v4, -v7, v3, v4
	v_fma_f32 v2, v6, v3, v10
	v_cvt_pk_bf16_f32 v3, v4, v2
	ds_write2_b32 v87, v9, v3 offset0:64 offset1:132
	ds_read2st64_b32 v[62:63], v73 offset0:18 offset1:19
	s_waitcnt lgkmcnt(2)
	v_fma_f32 v3, -v2, v7, v60
	v_fma_f32 v2, v2, v6, v61
	v_fma_f32 v2, v4, v7, v2
	v_fma_f32 v3, v4, v6, v3
	v_add_u32_e32 v74, 64, v70
	v_cvt_pk_bf16_f32 v4, v3, v2
	ds_read2st64_b32 v[64:65], v74 offset0:20 offset1:21
	s_waitcnt lgkmcnt(1)
	v_fma_f32 v5, -v2, v7, v62
	v_fma_f32 v2, v2, v6, v63
	v_fma_f32 v2, v3, v7, v2
	v_fma_f32 v5, v3, v6, v5
	v_cvt_pk_bf16_f32 v3, v5, v2
	v_add_u32_e32 v88, 0x2e00, v70
	v_add_u32_e32 v75, 0x50, v70
	ds_write2_b32 v88, v4, v3 offset0:72 offset1:140
	ds_read2st64_b32 v[66:67], v75 offset0:22 offset1:23
	s_waitcnt lgkmcnt(2)
	v_fma_f32 v4, v7, v5, v65
	v_fma_f32 v3, v6, v5, v64
	v_fma_f32 v3, -v7, v2, v3
	v_fma_f32 v2, v6, v2, v4
	v_add_u32_e32 v76, 0x60, v70
	v_cvt_pk_bf16_f32 v4, v3, v2
	ds_read2st64_b32 v[90:91], v76 offset0:24 offset1:25
	s_waitcnt lgkmcnt(1)
	v_fma_f32 v5, -v2, v7, v66
	v_fma_f32 v2, v2, v6, v67
	v_fma_f32 v2, v3, v7, v2
	v_fma_f32 v5, v3, v6, v5
	v_cvt_pk_bf16_f32 v3, v5, v2
	v_add_u32_e32 v89, 0x3000, v70
	v_add_u32_e32 v77, 0x70, v70
	ds_write2_b32 v89, v4, v3 offset0:80 offset1:148
	ds_read2st64_b32 v[92:93], v77 offset0:26 offset1:27
	s_waitcnt lgkmcnt(2)
	v_fma_f32 v4, v7, v5, v91
	v_fma_f32 v3, v6, v5, v90
	v_fma_f32 v3, -v7, v2, v3
	v_fma_f32 v2, v6, v2, v4
	v_add_u32_e32 v79, 0x80, v70
	v_cvt_pk_bf16_f32 v4, v3, v2
	ds_read2st64_b32 v[96:97], v79 offset0:28 offset1:29
	s_waitcnt lgkmcnt(1)
	v_fma_f32 v5, -v2, v7, v92
	v_fma_f32 v2, v2, v6, v93
	v_fma_f32 v2, v3, v7, v2
	v_fma_f32 v5, v3, v6, v5
	v_cvt_pk_bf16_f32 v3, v5, v2
	v_add_u32_e32 v90, 0x3200, v70
	v_add_u32_e32 v80, 0x90, v70
	ds_write2_b32 v90, v4, v3 offset0:88 offset1:156
	ds_read2st64_b32 v[98:99], v80 offset0:30 offset1:31
	s_waitcnt lgkmcnt(2)
	v_fma_f32 v4, v7, v5, v97
	v_fma_f32 v3, v6, v5, v96
	v_fma_f32 v3, -v7, v2, v3
	v_fma_f32 v2, v6, v2, v4
	v_add_u32_e32 v81, 0xa0, v70
	v_cvt_pk_bf16_f32 v4, v3, v2
	ds_read2st64_b32 v[100:101], v81 offset0:32 offset1:33
	s_waitcnt lgkmcnt(1)
	v_fma_f32 v5, -v2, v7, v98
	v_fma_f32 v2, v2, v6, v99
	v_fma_f32 v2, v3, v7, v2
	v_fma_f32 v5, v3, v6, v5
	v_cvt_pk_bf16_f32 v3, v5, v2
	v_add_u32_e32 v91, 0x3400, v70
	v_add_u32_e32 v82, 0xb0, v70
	ds_write2_b32 v91, v4, v3 offset0:96 offset1:164
	ds_read2st64_b32 v[102:103], v82 offset0:34 offset1:35
	s_waitcnt lgkmcnt(2)
	v_fma_f32 v4, v7, v5, v101
	v_fma_f32 v3, v6, v5, v100
	v_fma_f32 v3, -v7, v2, v3
	v_fma_f32 v2, v6, v2, v4
	v_add_u32_e32 v83, 0xc0, v70
	v_cvt_pk_bf16_f32 v4, v3, v2
	ds_read2st64_b32 v[104:105], v83 offset0:36 offset1:37
	s_waitcnt lgkmcnt(1)
	v_fma_f32 v5, -v2, v7, v102
	v_fma_f32 v2, v2, v6, v103
	v_fma_f32 v2, v3, v7, v2
	v_fma_f32 v5, v3, v6, v5
	v_cvt_pk_bf16_f32 v3, v5, v2
	v_add_u32_e32 v92, 0x3600, v70
	v_add_u32_e32 v84, 0xd0, v70
	ds_write2_b32 v92, v4, v3 offset0:104 offset1:172
	ds_read2st64_b32 v[106:107], v84 offset0:38 offset1:39
	s_waitcnt lgkmcnt(2)
	v_fma_f32 v4, v7, v5, v105
	v_fma_f32 v3, v6, v5, v104
	v_fma_f32 v3, -v7, v2, v3
	v_fma_f32 v2, v6, v2, v4
	v_add_u32_e32 v85, 0xe0, v70
	v_cvt_pk_bf16_f32 v4, v3, v2
	ds_read2st64_b32 v[108:109], v85 offset0:40 offset1:41
	s_waitcnt lgkmcnt(1)
	v_fma_f32 v5, -v2, v7, v106
	v_fma_f32 v2, v2, v6, v107
	v_fma_f32 v2, v3, v7, v2
	v_fma_f32 v5, v3, v6, v5
	v_cvt_pk_bf16_f32 v3, v5, v2
	v_add_u32_e32 v93, 0x3800, v70
	v_add_u32_e32 v86, 0xf0, v70
	ds_write2_b32 v93, v4, v3 offset0:112 offset1:180
	ds_read2st64_b32 v[110:111], v86 offset0:42 offset1:43
	s_waitcnt lgkmcnt(2)
	v_fma_f32 v4, v7, v5, v109
	v_fma_f32 v3, v6, v5, v108
	v_fma_f32 v3, -v7, v2, v3
	v_fma_f32 v2, v6, v2, v4
	v_cvt_pk_bf16_f32 v4, v3, v2
	s_waitcnt lgkmcnt(0)
	v_fma_f32 v5, v7, v3, v111
	v_fma_f32 v60, v6, v3, v110
	v_fma_f32 v60, -v7, v2, v60
	v_fma_f32 v61, v6, v2, v5
	v_cvt_pk_bf16_f32 v2, v60, v61
	v_add_u32_e32 v94, 0x3a00, v70
	ds_write2_b32 v94, v4, v2 offset0:120 offset1:188
	s_waitcnt lgkmcnt(0)
	v_add_u32_e32 v0, v112, v0
	ds_read_b128 v[2:5], v0 offset:11520
	ds_read_b128 v[62:65], v0 offset:11584
	s_waitcnt lgkmcnt(1)
	v_mfma_f32_16x16x32_bf16 v[2:5], v[2:5], v[24:27], 0
	ds_read_b128 v[96:99], v0 offset:11648
	v_mov_b32_e32 v9, 0
	v_mov_b32_e32 v10, 0
	s_waitcnt lgkmcnt(1)
	v_mfma_f32_16x16x32_bf16 v[2:5], v[62:65], v[20:23], v[2:5]
	ds_read_b128 v[62:65], v0 offset:11712
	v_mov_b32_e32 v11, 0
	s_waitcnt lgkmcnt(1)
	v_mfma_f32_16x16x32_bf16 v[2:5], v[96:99], v[16:19], v[2:5]
	s_waitcnt lgkmcnt(0)
	v_mfma_f32_16x16x32_bf16 v[2:5], v[62:65], v[12:15], v[2:5]
	s_and_saveexec_b64 s[8:9], vcc
	ds_read_b128 v[8:11], v95 offset:768
	s_or_b64 exec, exec, s[8:9]
	s_waitcnt lgkmcnt(0)
	v_mfma_f32_16x16x32_bf16 v[62:65], v[8:11], v[52:55], 0
	v_mul_f32_e32 v118, v7, v61
	v_fma_f32 v118, v6, v60, -v118
	v_mul_f32_e32 v60, v7, v60
	v_mfma_f32_16x16x32_bf16 v[96:99], v[8:11], v[56:59], 0
	s_nop 7
	ds_write2_b32 v68, v62, v96 offset1:16
	ds_write2_b32 v68, v63, v97 offset0:132 offset1:148
	ds_write2_b32 v69, v64, v98 offset0:8 offset1:24
	v_mfma_f32_16x16x32_bf16 v[100:103], v[8:11], v[44:47], 0
	v_fmac_f32_e32 v60, v6, v61
	v_mfma_f32_16x16x32_bf16 v[104:107], v[8:11], v[48:51], 0
	ds_write2_b32 v69, v65, v99 offset0:140 offset1:156
	s_nop 6
	ds_write2_b32 v68, v100, v104 offset0:32 offset1:48
	ds_write2_b32 v68, v101, v105 offset0:164 offset1:180
	v_mfma_f32_16x16x32_bf16 v[108:111], v[8:11], v[40:43], 0
	v_mfma_f32_16x16x32_bf16 v[62:65], v[8:11], v[36:39], 0
	ds_write2_b32 v69, v102, v106 offset0:40 offset1:56
	ds_write2_b32 v69, v103, v107 offset0:172 offset1:188
	s_nop 5
	ds_write2_b32 v68, v108, v62 offset0:64 offset1:80
	ds_write2_b32 v68, v109, v63 offset0:196 offset1:212
	ds_write2_b32 v69, v110, v64 offset0:72 offset1:88
	ds_write2_b32 v69, v111, v65 offset0:204 offset1:220
	v_mfma_f32_16x16x32_bf16 v[96:99], v[8:11], v[32:35], 0
	v_mfma_f32_16x16x32_bf16 v[8:11], v[8:11], v[28:31], 0
	s_nop 7
	ds_write2_b32 v68, v96, v8 offset0:96 offset1:112
	ds_write2_b32 v68, v97, v9 offset0:228 offset1:244
	ds_write2_b32 v69, v98, v10 offset0:104 offset1:120
	ds_write2_b32 v69, v99, v11 offset0:236 offset1:252
	s_waitcnt lgkmcnt(0)
	ds_read2st64_b32 v[8:9], v70 offset0:12 offset1:13
	ds_read2st64_b32 v[10:11], v71 offset0:14 offset1:15
	ds_read2st64_b32 v[62:63], v72 offset0:16 offset1:17
	ds_read2st64_b32 v[64:65], v73 offset0:18 offset1:19
	ds_read2st64_b32 v[66:67], v74 offset0:20 offset1:21
	ds_read2st64_b32 v[96:97], v75 offset0:22 offset1:23
	ds_read2st64_b32 v[98:99], v76 offset0:24 offset1:25
	ds_read2st64_b32 v[100:101], v77 offset0:26 offset1:27
	ds_read2st64_b32 v[102:103], v79 offset0:28 offset1:29
	ds_read2st64_b32 v[104:105], v80 offset0:30 offset1:31
	ds_read2st64_b32 v[106:107], v81 offset0:32 offset1:33
	ds_read2st64_b32 v[108:109], v82 offset0:34 offset1:35
	ds_read2st64_b32 v[110:111], v83 offset0:36 offset1:37
	ds_read2st64_b32 v[112:113], v84 offset0:38 offset1:39
	ds_read2st64_b32 v[114:115], v85 offset0:40 offset1:41
	ds_read2st64_b32 v[116:117], v86 offset0:42 offset1:43
	s_waitcnt lgkmcnt(14)
	v_add_f32_e32 v8, v118, v8
	v_add_f32_e32 v9, v60, v9
	v_cvt_pk_bf16_f32 v60, v8, v9
	v_fma_f32 v61, v7, v8, v11
	v_fma_f32 v10, v6, v8, v10
	v_fma_f32 v10, -v7, v9, v10
	v_fma_f32 v8, v6, v9, v61
	v_cvt_pk_bf16_f32 v9, v10, v8
	ds_write2_b32 v87, v60, v9 offset0:64 offset1:132
	s_waitcnt lgkmcnt(14)
	v_fma_f32 v9, -v8, v7, v62
	v_fma_f32 v8, v8, v6, v63
	v_fma_f32 v8, v10, v7, v8
	v_fma_f32 v9, v10, v6, v9
	v_cvt_pk_bf16_f32 v10, v9, v8
	s_waitcnt lgkmcnt(13)
	v_fma_f32 v11, -v8, v7, v64
	v_fma_f32 v8, v8, v6, v65
	v_fma_f32 v8, v9, v7, v8
	v_fma_f32 v11, v9, v6, v11
	v_cvt_pk_bf16_f32 v9, v11, v8
	ds_write2_b32 v88, v10, v9 offset0:72 offset1:140
	s_waitcnt lgkmcnt(13)
	v_fma_f32 v10, v7, v11, v67
	v_fma_f32 v9, v6, v11, v66
	v_fma_f32 v9, -v7, v8, v9
	v_fma_f32 v8, v6, v8, v10
	v_cvt_pk_bf16_f32 v10, v9, v8
	s_waitcnt lgkmcnt(12)
	v_fma_f32 v11, -v8, v7, v96
	v_fma_f32 v8, v8, v6, v97
	v_fma_f32 v8, v9, v7, v8
	v_fma_f32 v11, v9, v6, v11
	v_cvt_pk_bf16_f32 v9, v11, v8
	ds_write2_b32 v89, v10, v9 offset0:80 offset1:148
	s_waitcnt lgkmcnt(12)
	v_fma_f32 v10, v7, v11, v99
	v_fma_f32 v9, v6, v11, v98
	v_fma_f32 v9, -v7, v8, v9
	v_fma_f32 v8, v6, v8, v10
	v_cvt_pk_bf16_f32 v10, v9, v8
	s_waitcnt lgkmcnt(11)
	v_fma_f32 v11, -v8, v7, v100
	v_fma_f32 v8, v8, v6, v101
	v_fma_f32 v8, v9, v7, v8
	v_fma_f32 v11, v9, v6, v11
	v_cvt_pk_bf16_f32 v9, v11, v8
	ds_write2_b32 v90, v10, v9 offset0:88 offset1:156
	s_waitcnt lgkmcnt(11)
	v_fma_f32 v10, v7, v11, v103
	v_fma_f32 v9, v6, v11, v102
	v_fma_f32 v9, -v7, v8, v9
	v_fma_f32 v8, v6, v8, v10
	v_cvt_pk_bf16_f32 v10, v9, v8
	s_waitcnt lgkmcnt(10)
	v_fma_f32 v11, -v8, v7, v104
	v_fma_f32 v8, v8, v6, v105
	v_fma_f32 v8, v9, v7, v8
	v_fma_f32 v11, v9, v6, v11
	v_cvt_pk_bf16_f32 v9, v11, v8
	ds_write2_b32 v91, v10, v9 offset0:96 offset1:164
	s_waitcnt lgkmcnt(10)
	v_fma_f32 v10, v7, v11, v107
	v_fma_f32 v9, v6, v11, v106
	v_fma_f32 v9, -v7, v8, v9
	v_fma_f32 v8, v6, v8, v10
	v_cvt_pk_bf16_f32 v10, v9, v8
	s_waitcnt lgkmcnt(9)
	v_fma_f32 v11, -v8, v7, v108
	v_fma_f32 v8, v8, v6, v109
	v_fma_f32 v8, v9, v7, v8
	v_fma_f32 v11, v9, v6, v11
	v_cvt_pk_bf16_f32 v9, v11, v8
	ds_write2_b32 v92, v10, v9 offset0:104 offset1:172
	s_waitcnt lgkmcnt(9)
	v_fma_f32 v10, v7, v11, v111
	v_fma_f32 v9, v6, v11, v110
	v_fma_f32 v9, -v7, v8, v9
	v_fma_f32 v8, v6, v8, v10
	v_cvt_pk_bf16_f32 v10, v9, v8
	s_waitcnt lgkmcnt(8)
	v_fma_f32 v11, -v8, v7, v112
	v_fma_f32 v8, v8, v6, v113
	v_fma_f32 v8, v9, v7, v8
	v_fma_f32 v11, v9, v6, v11
	v_cvt_pk_bf16_f32 v9, v11, v8
	ds_write2_b32 v93, v10, v9 offset0:112 offset1:180
	s_waitcnt lgkmcnt(8)
	v_fma_f32 v10, v7, v11, v115
	v_fma_f32 v9, v6, v11, v114
	v_fma_f32 v9, -v7, v8, v9
	v_fma_f32 v8, v6, v8, v10
	v_cvt_pk_bf16_f32 v10, v9, v8
	s_waitcnt lgkmcnt(7)
	v_fma_f32 v11, v7, v9, v117
	v_fma_f32 v65, v6, v9, v116
	v_fma_f32 v65, -v7, v8, v65
	v_fma_f32 v66, v6, v8, v11
	v_cvt_pk_bf16_f32 v8, v65, v66
	ds_write2_b32 v94, v10, v8 offset0:120 offset1:188
	s_waitcnt lgkmcnt(0)
	ds_read_b128 v[8:11], v0 offset:11520
	ds_read_b128 v[60:63], v0 offset:11584
	s_waitcnt lgkmcnt(1)
	v_mfma_f32_16x16x32_bf16 v[8:11], v[8:11], v[24:27], 0
	ds_read_b128 v[96:99], v0 offset:11648
	v_mov_b32_e32 v64, 0
	s_waitcnt lgkmcnt(1)
	v_mfma_f32_16x16x32_bf16 v[8:11], v[60:63], v[20:23], v[8:11]
	ds_read_b128 v[60:63], v0 offset:11712
	s_waitcnt lgkmcnt(1)
	v_mfma_f32_16x16x32_bf16 v[8:11], v[96:99], v[16:19], v[8:11]
	s_waitcnt lgkmcnt(0)
	v_mfma_f32_16x16x32_bf16 v[8:11], v[60:63], v[12:15], v[8:11]
	v_mov_b32_e32 v60, 0
	v_mov_b32_e32 v61, 0
	v_mov_b32_e32 v62, 0
	v_mov_b32_e32 v63, 0
	s_and_saveexec_b64 s[8:9], vcc
	ds_read_b128 v[60:63], v95 offset:1536
	s_or_b64 exec, exec, s[8:9]
	s_waitcnt lgkmcnt(0)
	v_mfma_f32_16x16x32_bf16 v[96:99], v[60:63], v[52:55], 0
	v_mul_f32_e32 v67, v7, v66
	v_fma_f32 v67, v6, v65, -v67
	v_mul_f32_e32 v65, v7, v65
	v_mfma_f32_16x16x32_bf16 v[100:103], v[60:63], v[56:59], 0
	s_nop 7
	ds_write2_b32 v68, v96, v100 offset1:16
	ds_write2_b32 v68, v97, v101 offset0:132 offset1:148
	ds_write2_b32 v69, v98, v102 offset0:8 offset1:24
	v_mfma_f32_16x16x32_bf16 v[104:107], v[60:63], v[44:47], 0
	v_fmac_f32_e32 v65, v6, v66
	v_mfma_f32_16x16x32_bf16 v[108:111], v[60:63], v[48:51], 0
	ds_write2_b32 v69, v99, v103 offset0:140 offset1:156
	s_nop 6
	ds_write2_b32 v68, v104, v108 offset0:32 offset1:48
	ds_write2_b32 v68, v105, v109 offset0:164 offset1:180
	v_mfma_f32_16x16x32_bf16 v[112:115], v[60:63], v[40:43], 0
	v_mfma_f32_16x16x32_bf16 v[96:99], v[60:63], v[36:39], 0
	ds_write2_b32 v69, v106, v110 offset0:40 offset1:56
	ds_write2_b32 v69, v107, v111 offset0:172 offset1:188
	s_nop 5
	ds_write2_b32 v68, v112, v96 offset0:64 offset1:80
	ds_write2_b32 v68, v113, v97 offset0:196 offset1:212
	ds_write2_b32 v69, v114, v98 offset0:72 offset1:88
	ds_write2_b32 v69, v115, v99 offset0:204 offset1:220
	v_mfma_f32_16x16x32_bf16 v[100:103], v[60:63], v[32:35], 0
	v_mfma_f32_16x16x32_bf16 v[60:63], v[60:63], v[28:31], 0
	s_nop 7
	ds_write2_b32 v68, v100, v60 offset0:96 offset1:112
	ds_write2_b32 v68, v101, v61 offset0:228 offset1:244
	ds_write2_b32 v69, v102, v62 offset0:104 offset1:120
	ds_write2_b32 v69, v103, v63 offset0:236 offset1:252
	s_waitcnt lgkmcnt(0)
	ds_read2st64_b32 v[60:61], v70 offset0:12 offset1:13
	ds_read2st64_b32 v[62:63], v71 offset0:14 offset1:15
	ds_read2st64_b32 v[96:97], v72 offset0:16 offset1:17
	ds_read2st64_b32 v[98:99], v73 offset0:18 offset1:19
	ds_read2st64_b32 v[100:101], v74 offset0:20 offset1:21
	ds_read2st64_b32 v[102:103], v75 offset0:22 offset1:23
	ds_read2st64_b32 v[104:105], v76 offset0:24 offset1:25
	ds_read2st64_b32 v[106:107], v77 offset0:26 offset1:27
	ds_read2st64_b32 v[108:109], v79 offset0:28 offset1:29
	ds_read2st64_b32 v[110:111], v80 offset0:30 offset1:31
	ds_read2st64_b32 v[112:113], v81 offset0:32 offset1:33
	ds_read2st64_b32 v[114:115], v82 offset0:34 offset1:35
	ds_read2st64_b32 v[116:117], v83 offset0:36 offset1:37
	ds_read2st64_b32 v[118:119], v84 offset0:38 offset1:39
	ds_read2st64_b32 v[120:121], v85 offset0:40 offset1:41
	ds_read2st64_b32 v[122:123], v86 offset0:42 offset1:43
	s_waitcnt lgkmcnt(14)
	v_add_f32_e32 v60, v67, v60
	v_add_f32_e32 v61, v65, v61
	v_cvt_pk_bf16_f32 v65, v60, v61
	v_fma_f32 v66, v7, v60, v63
	v_fma_f32 v62, v6, v60, v62
	v_fma_f32 v62, -v7, v61, v62
	v_fma_f32 v60, v6, v61, v66
	v_cvt_pk_bf16_f32 v61, v62, v60
	ds_write2_b32 v87, v65, v61 offset0:64 offset1:132
	s_waitcnt lgkmcnt(14)
	v_fma_f32 v61, -v60, v7, v96
	v_fma_f32 v60, v60, v6, v97
	v_fma_f32 v60, v62, v7, v60
	v_fma_f32 v61, v62, v6, v61
	v_cvt_pk_bf16_f32 v62, v61, v60
	s_waitcnt lgkmcnt(13)
	v_fma_f32 v63, -v60, v7, v98
	v_fma_f32 v60, v60, v6, v99
	v_fma_f32 v60, v61, v7, v60
	v_fma_f32 v63, v61, v6, v63
	v_cvt_pk_bf16_f32 v61, v63, v60
	ds_write2_b32 v88, v62, v61 offset0:72 offset1:140
	s_waitcnt lgkmcnt(13)
	v_fma_f32 v62, v7, v63, v101
	v_fma_f32 v61, v6, v63, v100
	v_fma_f32 v61, -v7, v60, v61
	v_fma_f32 v60, v6, v60, v62
	v_cvt_pk_bf16_f32 v62, v61, v60
	s_waitcnt lgkmcnt(12)
	v_fma_f32 v63, -v60, v7, v102
	v_fma_f32 v60, v60, v6, v103
	v_fma_f32 v60, v61, v7, v60
	v_fma_f32 v63, v61, v6, v63
	v_cvt_pk_bf16_f32 v61, v63, v60
	ds_write2_b32 v89, v62, v61 offset0:80 offset1:148
	s_waitcnt lgkmcnt(12)
	v_fma_f32 v62, v7, v63, v105
	v_fma_f32 v61, v6, v63, v104
	v_fma_f32 v61, -v7, v60, v61
	v_fma_f32 v60, v6, v60, v62
	v_cvt_pk_bf16_f32 v62, v61, v60
	s_waitcnt lgkmcnt(11)
	v_fma_f32 v63, -v60, v7, v106
	v_fma_f32 v60, v60, v6, v107
	v_fma_f32 v60, v61, v7, v60
	v_fma_f32 v63, v61, v6, v63
	v_cvt_pk_bf16_f32 v61, v63, v60
	ds_write2_b32 v90, v62, v61 offset0:88 offset1:156
	s_waitcnt lgkmcnt(11)
	v_fma_f32 v62, v7, v63, v109
	v_fma_f32 v61, v6, v63, v108
	v_fma_f32 v61, -v7, v60, v61
	v_fma_f32 v60, v6, v60, v62
	v_cvt_pk_bf16_f32 v62, v61, v60
	s_waitcnt lgkmcnt(10)
	v_fma_f32 v63, -v60, v7, v110
	v_fma_f32 v60, v60, v6, v111
	v_fma_f32 v60, v61, v7, v60
	v_fma_f32 v63, v61, v6, v63
	v_cvt_pk_bf16_f32 v61, v63, v60
	ds_write2_b32 v91, v62, v61 offset0:96 offset1:164
	s_waitcnt lgkmcnt(10)
	v_fma_f32 v62, v7, v63, v113
	v_fma_f32 v61, v6, v63, v112
	v_fma_f32 v61, -v7, v60, v61
	v_fma_f32 v60, v6, v60, v62
	v_cvt_pk_bf16_f32 v62, v61, v60
	s_waitcnt lgkmcnt(9)
	v_fma_f32 v63, -v60, v7, v114
	v_fma_f32 v60, v60, v6, v115
	v_fma_f32 v60, v61, v7, v60
	v_fma_f32 v63, v61, v6, v63
	v_cvt_pk_bf16_f32 v61, v63, v60
	ds_write2_b32 v92, v62, v61 offset0:104 offset1:172
	s_waitcnt lgkmcnt(9)
	v_fma_f32 v62, v7, v63, v117
	v_fma_f32 v61, v6, v63, v116
	v_fma_f32 v61, -v7, v60, v61
	v_fma_f32 v60, v6, v60, v62
	v_cvt_pk_bf16_f32 v62, v61, v60
	s_waitcnt lgkmcnt(8)
	v_fma_f32 v63, -v60, v7, v118
	v_fma_f32 v60, v60, v6, v119
	v_fma_f32 v60, v61, v7, v60
	v_fma_f32 v63, v61, v6, v63
	v_cvt_pk_bf16_f32 v61, v63, v60
	ds_write2_b32 v93, v62, v61 offset0:112 offset1:180
	s_waitcnt lgkmcnt(8)
	v_fma_f32 v62, v7, v63, v121
	v_fma_f32 v61, v6, v63, v120
	v_fma_f32 v61, -v7, v60, v61
	v_fma_f32 v60, v6, v60, v62
	v_cvt_pk_bf16_f32 v62, v61, v60
	s_waitcnt lgkmcnt(7)
	v_fma_f32 v63, v7, v61, v123
	v_fma_f32 v96, v6, v61, v122
	v_fma_f32 v96, -v7, v60, v96
	v_fma_f32 v97, v6, v60, v63
	v_cvt_pk_bf16_f32 v60, v96, v97
	ds_write2_b32 v94, v62, v60 offset0:120 offset1:188
	s_waitcnt lgkmcnt(0)
	ds_read_b128 v[60:63], v0 offset:11520
	ds_read_b128 v[98:101], v0 offset:11584
	s_waitcnt lgkmcnt(1)
	v_mfma_f32_16x16x32_bf16 v[60:63], v[60:63], v[24:27], 0
	ds_read_b128 v[102:105], v0 offset:11648
	v_mov_b32_e32 v65, 0
	v_mov_b32_e32 v66, 0
	s_waitcnt lgkmcnt(1)
	v_mfma_f32_16x16x32_bf16 v[60:63], v[98:101], v[20:23], v[60:63]
	ds_read_b128 v[98:101], v0 offset:11712
	v_mov_b32_e32 v67, 0
	s_waitcnt lgkmcnt(1)
	v_mfma_f32_16x16x32_bf16 v[60:63], v[102:105], v[16:19], v[60:63]
	s_waitcnt lgkmcnt(0)
	v_mfma_f32_16x16x32_bf16 v[60:63], v[98:101], v[12:15], v[60:63]
	s_and_saveexec_b64 s[8:9], vcc
	ds_read_b128 v[64:67], v95 offset:2304
	s_or_b64 exec, exec, s[8:9]
	s_waitcnt lgkmcnt(0)
	v_mfma_f32_16x16x32_bf16 v[52:55], v[64:67], v[52:55], 0
	s_mov_b32 s9, 0x200000
	v_mfma_f32_16x16x32_bf16 v[56:59], v[64:67], v[56:59], 0
	s_nop 7
	ds_write2_b32 v68, v52, v56 offset1:16
	ds_write2_b32 v68, v53, v57 offset0:132 offset1:148
	ds_write2_b32 v69, v54, v58 offset0:8 offset1:24
	ds_write2_b32 v69, v55, v59 offset0:140 offset1:156
	v_mfma_f32_16x16x32_bf16 v[44:47], v[64:67], v[44:47], 0
	v_mfma_f32_16x16x32_bf16 v[48:51], v[64:67], v[48:51], 0
	s_nop 7
	ds_write2_b32 v68, v44, v48 offset0:32 offset1:48
	ds_write2_b32 v68, v45, v49 offset0:164 offset1:180
	ds_write2_b32 v69, v46, v50 offset0:40 offset1:56
	ds_write2_b32 v69, v47, v51 offset0:172 offset1:188
	v_mfma_f32_16x16x32_bf16 v[40:43], v[64:67], v[40:43], 0
	v_mfma_f32_16x16x32_bf16 v[36:39], v[64:67], v[36:39], 0
	s_nop 7
	ds_write2_b32 v68, v40, v36 offset0:64 offset1:80
	ds_write2_b32 v68, v41, v37 offset0:196 offset1:212
	ds_write2_b32 v69, v42, v38 offset0:72 offset1:88
	ds_write2_b32 v69, v43, v39 offset0:204 offset1:220
	v_mfma_f32_16x16x32_bf16 v[32:35], v[64:67], v[32:35], 0
	v_mfma_f32_16x16x32_bf16 v[28:31], v[64:67], v[28:31], 0
	s_nop 7
	ds_write2_b32 v68, v32, v28 offset0:96 offset1:112
	ds_write2_b32 v68, v33, v29 offset0:228 offset1:244
	ds_write2_b32 v69, v34, v30 offset0:104 offset1:120
	ds_write2_b32 v69, v35, v31 offset0:236 offset1:252
	s_waitcnt lgkmcnt(0)
	v_mul_f32_e32 v64, v7, v97
	ds_read2st64_b32 v[28:29], v70 offset0:12 offset1:13
	ds_read2st64_b32 v[30:31], v71 offset0:14 offset1:15
	ds_read2st64_b32 v[32:33], v72 offset0:16 offset1:17
	ds_read2st64_b32 v[34:35], v73 offset0:18 offset1:19
	ds_read2st64_b32 v[36:37], v74 offset0:20 offset1:21
	ds_read2st64_b32 v[38:39], v75 offset0:22 offset1:23
	ds_read2st64_b32 v[40:41], v76 offset0:24 offset1:25
	ds_read2st64_b32 v[42:43], v77 offset0:26 offset1:27
	ds_read2st64_b32 v[44:45], v79 offset0:28 offset1:29
	ds_read2st64_b32 v[46:47], v80 offset0:30 offset1:31
	ds_read2st64_b32 v[48:49], v81 offset0:32 offset1:33
	ds_read2st64_b32 v[50:51], v82 offset0:34 offset1:35
	ds_read2st64_b32 v[52:53], v83 offset0:36 offset1:37
	ds_read2st64_b32 v[54:55], v84 offset0:38 offset1:39
	ds_read2st64_b32 v[56:57], v85 offset0:40 offset1:41
	ds_read2st64_b32 v[58:59], v86 offset0:42 offset1:43
	v_fma_f32 v64, v6, v96, -v64
	s_waitcnt lgkmcnt(14)
	v_add_f32_e32 v28, v64, v28
	v_mul_f32_e32 v64, v7, v96
	v_fmac_f32_e32 v64, v6, v97
	v_add_f32_e32 v29, v64, v29
	v_cvt_pk_bf16_f32 v64, v28, v29
	v_fma_f32 v65, v7, v28, v31
	v_fma_f32 v30, v6, v28, v30
	v_fma_f32 v30, -v7, v29, v30
	v_fma_f32 v28, v6, v29, v65
	v_cvt_pk_bf16_f32 v29, v30, v28
	ds_write2_b32 v87, v64, v29 offset0:64 offset1:132
	s_waitcnt lgkmcnt(14)
	v_fma_f32 v29, -v28, v7, v32
	v_fma_f32 v28, v28, v6, v33
	v_fma_f32 v28, v30, v7, v28
	v_fma_f32 v29, v30, v6, v29
	v_cvt_pk_bf16_f32 v30, v29, v28
	s_waitcnt lgkmcnt(13)
	v_fma_f32 v31, -v28, v7, v34
	v_fma_f32 v28, v28, v6, v35
	v_fma_f32 v28, v29, v7, v28
	v_fma_f32 v31, v29, v6, v31
	v_cvt_pk_bf16_f32 v29, v31, v28
	ds_write2_b32 v88, v30, v29 offset0:72 offset1:140
	s_waitcnt lgkmcnt(13)
	v_fma_f32 v30, v7, v31, v37
	v_fma_f32 v29, v6, v31, v36
	v_fma_f32 v29, -v7, v28, v29
	v_fma_f32 v28, v6, v28, v30
	v_cvt_pk_bf16_f32 v30, v29, v28
	s_waitcnt lgkmcnt(12)
	v_fma_f32 v31, -v28, v7, v38
	v_fma_f32 v28, v28, v6, v39
	v_fma_f32 v28, v29, v7, v28
	v_fma_f32 v31, v29, v6, v31
	v_cvt_pk_bf16_f32 v29, v31, v28
	ds_write2_b32 v89, v30, v29 offset0:80 offset1:148
	s_waitcnt lgkmcnt(12)
	v_fma_f32 v30, v7, v31, v41
	v_fma_f32 v29, v6, v31, v40
	v_fma_f32 v29, -v7, v28, v29
	v_fma_f32 v28, v6, v28, v30
	v_cvt_pk_bf16_f32 v30, v29, v28
	s_waitcnt lgkmcnt(11)
	v_fma_f32 v31, -v28, v7, v42
	v_fma_f32 v28, v28, v6, v43
	v_fma_f32 v28, v29, v7, v28
	v_fma_f32 v31, v29, v6, v31
	v_cvt_pk_bf16_f32 v29, v31, v28
	ds_write2_b32 v90, v30, v29 offset0:88 offset1:156
	s_waitcnt lgkmcnt(11)
	v_fma_f32 v30, v7, v31, v45
	v_fma_f32 v29, v6, v31, v44
	v_fma_f32 v29, -v7, v28, v29
	v_fma_f32 v28, v6, v28, v30
	v_cvt_pk_bf16_f32 v30, v29, v28
	s_waitcnt lgkmcnt(10)
	v_fma_f32 v31, -v28, v7, v46
	v_fma_f32 v28, v28, v6, v47
	v_fma_f32 v28, v29, v7, v28
	v_fma_f32 v31, v29, v6, v31
	v_cvt_pk_bf16_f32 v29, v31, v28
	ds_write2_b32 v91, v30, v29 offset0:96 offset1:164
	s_waitcnt lgkmcnt(10)
	v_fma_f32 v30, v7, v31, v49
	v_fma_f32 v29, v6, v31, v48
	v_fma_f32 v29, -v7, v28, v29
	v_fma_f32 v28, v6, v28, v30
	v_cvt_pk_bf16_f32 v30, v29, v28
	s_waitcnt lgkmcnt(9)
	v_fma_f32 v31, -v28, v7, v50
	v_fma_f32 v28, v28, v6, v51
	v_fma_f32 v28, v29, v7, v28
	v_fma_f32 v31, v29, v6, v31
	v_cvt_pk_bf16_f32 v29, v31, v28
	ds_write2_b32 v92, v30, v29 offset0:104 offset1:172
	s_waitcnt lgkmcnt(9)
	v_fma_f32 v30, v7, v31, v53
	v_fma_f32 v29, v6, v31, v52
	v_fma_f32 v29, -v7, v28, v29
	v_fma_f32 v28, v6, v28, v30
	v_cvt_pk_bf16_f32 v30, v29, v28
	s_waitcnt lgkmcnt(8)
	v_fma_f32 v31, -v28, v7, v54
	v_fma_f32 v28, v28, v6, v55
	v_fma_f32 v28, v29, v7, v28
	v_fma_f32 v31, v29, v6, v31
	v_cvt_pk_bf16_f32 v29, v31, v28
	ds_write2_b32 v93, v30, v29 offset0:112 offset1:180
	s_waitcnt lgkmcnt(8)
	v_fma_f32 v30, v7, v31, v57
	v_fma_f32 v29, v6, v31, v56
	v_fma_f32 v29, -v7, v28, v29
	v_fma_f32 v28, v6, v28, v30
	v_mul_f32_e32 v31, v7, v28
	v_mul_f32_e32 v7, v7, v29
	v_fma_f32 v31, v6, v29, -v31
	v_fmac_f32_e32 v7, v6, v28
	s_waitcnt lgkmcnt(7)
	v_add_f32_e32 v31, v58, v31
	v_add_f32_e32 v6, v59, v7
	v_cvt_pk_bf16_f32 v30, v29, v28
	v_cvt_pk_bf16_f32 v6, v31, v6
	ds_write2_b32 v94, v30, v6 offset0:120 offset1:188
	s_waitcnt lgkmcnt(0)
	ds_read_b128 v[28:31], v0 offset:11520
	s_waitcnt lgkmcnt(0)
	v_mfma_f32_16x16x32_bf16 v[24:27], v[28:31], v[24:27], 0
	ds_read_b128 v[28:31], v0 offset:11584
	v_mov_b32_e32 v73, v204
	v_mov_b32_e32 v72, 0
	s_waitcnt lgkmcnt(0)
	v_mfma_f32_16x16x32_bf16 v[20:23], v[28:31], v[20:23], v[24:27]
	s_nop 2
	ds_read_b128 v[24:27], v0 offset:11648
	v_mov_b32_e32 v75, 0
	v_mov_b32_e32 v76, 0
	s_waitcnt lgkmcnt(0)
	v_mfma_f32_16x16x32_bf16 v[16:19], v[24:27], v[16:19], v[20:23]
	s_nop 2
	ds_read_b128 v[20:23], v0 offset:11712
	v_mov_b32_e32 v0, s59
	ds_read_b64 v[6:7], v0
	v_readfirstlane_b32 s5, v73
	s_lshr_b32 s5, s5, 6
	s_mulk_i32 s5, 0x3e00
	s_add_i32 s8, s5, 0
	v_readlane_b32 s5, v244, 25
	v_and_b32_e32 v59, 63, v73
	s_add_i32 s28, s4, s5
	s_waitcnt lgkmcnt(0)
	v_readfirstlane_b32 s4, v6
	v_lshl_or_b32 v6, s28, 6, v59
	v_readfirstlane_b32 s5, v7
	v_ashrrev_i32_e32 v7, 31, v6
	s_ashr_i32 s29, s28, 31
	v_lshl_add_u64 v[6:7], v[6:7], 4, s[4:5]
	s_lshl_b64 s[38:39], s[28:29], 13
	v_add_co_u32_e32 v6, vcc, s9, v6
	s_add_u32 s38, s4, s38
	v_and_b32_e32 v58, 15, v73
	v_addc_co_u32_e32 v7, vcc, 0, v7, vcc
	s_addc_u32 s39, s5, s39
	v_and_b32_e32 v0, 48, v73
	v_mfma_f32_16x16x32_bf16 v[12:15], v[20:23], v[12:15], v[16:19]
	global_load_dwordx2 v[32:33], v[6:7], off
	v_lshl_add_u64 v[6:7], s[38:39], 0, v[0:1]
	s_mov_b32 s9, 0x240000
	v_lshlrev_b32_e32 v16, 6, v58
	v_mov_b32_e32 v17, v1
	v_lshl_add_u64 v[6:7], v[6:7], 0, v[16:17]
	v_add_co_u32_e32 v18, vcc, s9, v6
	s_mov_b64 s[38:39], 0x240000
	s_nop 0
	v_addc_co_u32_e32 v19, vcc, 0, v7, vcc
	s_mov_b32 s9, 0x241000
	v_lshl_add_u64 v[16:17], v[6:7], 0, s[38:39]
	v_add_co_u32_e32 v6, vcc, s9, v6
	s_lshl_b64 s[28:29], s[28:29], 12
	s_nop 0
	v_addc_co_u32_e32 v7, vcc, 0, v7, vcc
	s_add_u32 s28, s4, s28
	global_load_dwordx4 v[42:45], v[18:19], off
	global_load_dwordx4 v[68:71], v[16:17], off offset:1024
	global_load_dwordx4 v[64:67], v[16:17], off offset:2048
	global_load_dwordx4 v[50:53], v[16:17], off offset:3072
	global_load_dwordx4 v[54:57], v[6:7], off
	global_load_dwordx4 v[46:49], v[6:7], off offset:1024
	global_load_dwordx4 v[38:41], v[6:7], off offset:2048
	s_waitcnt lgkmcnt(0)
	global_load_dwordx4 v[34:37], v[6:7], off offset:3072
	s_addc_u32 s29, s5, s29
	v_lshlrev_b32_e32 v6, 8, v58
	v_mov_b32_e32 v7, v1
	v_lshl_add_u64 v[6:7], s[28:29], 0, v[6:7]
	v_lshl_add_u64 v[6:7], v[6:7], 0, v[0:1]
	s_mov_b64 s[28:29], 0x380000
	s_mov_b32 s9, 0x380000
	v_lshl_add_u64 v[16:17], v[6:7], 0, s[28:29]
	v_add_co_u32_e32 v6, vcc, s9, v6
	s_or_b32 s9, s26, 1
	s_mul_hi_i32 s28, s9, 0x44
	s_mulk_i32 s9, 0x44
	s_add_u32 s26, s9, s22
	s_addc_u32 s27, s28, s27
	s_lshl_b64 s[26:27], s[26:27], 10
	s_add_u32 s6, s26, s6
	v_addc_co_u32_e32 v7, vcc, 0, v7, vcc
	s_addc_u32 s7, s27, s7
	global_load_dwordx4 v[20:23], v[6:7], off
	global_load_dwordx4 v[28:31], v[16:17], off offset:64
	global_load_dwordx4 v[24:27], v[16:17], off offset:128
	s_nop 0
	global_load_dwordx4 v[16:19], v[16:17], off offset:192
	v_or_b32_e32 v6, s6, v59
	v_mov_b32_e32 v7, s7
	v_lshl_add_u64 v[6:7], v[6:7], 3, s[4:5]
	v_add_co_u32_e32 v6, vcc, 0x1500000, v6
	v_add_u32_e32 v74, s8, v0
	s_nop 0
	v_addc_co_u32_e32 v7, vcc, 0, v7, vcc
	global_load_dwordx2 v[6:7], v[6:7], off
	v_cmp_gt_u32_e32 vcc, 32, v59
	v_mad_u32_u24 v81, v58, 48, v74
	v_mov_b32_e32 v74, 0
	v_mov_b32_e32 v77, 0
	s_and_saveexec_b64 s[4:5], vcc
	ds_read_b128 v[74:77], v81 offset:2304
	s_or_b64 exec, exec, s[4:5]
	s_waitcnt vmcnt(6) lgkmcnt(0)
	v_mfma_f32_16x16x32_bf16 v[82:85], v[74:77], v[42:45], 0
	v_bfe_u32 v73, v73, 4, 2
	v_mov_b32_e32 v80, s8
	s_movk_i32 s4, 0x110
	v_mfma_f32_16x16x32_bf16 v[86:89], v[74:77], v[68:71], 0
	v_lshlrev_b32_e32 v79, 2, v58
	v_mad_u32_u24 v126, v58, s4, v80
	v_mul_u32_u24_e32 v58, 0x840, v73
	v_mfma_f32_16x16x32_bf16 v[90:93], v[74:77], v[64:67], 0
	v_add3_u32 v58, s8, v79, v58
	v_add_u32_e32 v80, 0xc00, v58
	s_nop 1
	ds_write2_b32 v80, v82, v86 offset1:16
	v_mfma_f32_16x16x32_bf16 v[94:97], v[74:77], v[50:53], 0
	v_add_u32_e32 v82, 0x1000, v58
	ds_write2_b32 v80, v83, v87 offset0:132 offset1:148
	ds_write2_b32 v82, v84, v88 offset0:8 offset1:24
	v_mfma_f32_16x16x32_bf16 v[98:101], v[74:77], v[54:57], 0
	ds_write2_b32 v82, v85, v89 offset0:140 offset1:156
	s_nop 2
	ds_write2_b32 v80, v90, v94 offset0:32 offset1:48
	ds_write2_b32 v80, v91, v95 offset0:164 offset1:180
	v_lshlrev_b32_e32 v59, 2, v59
	v_add_u32_e32 v83, s8, v59
	v_mfma_f32_16x16x32_bf16 v[84:87], v[74:77], v[46:49], 0
	ds_write2_b32 v82, v92, v96 offset0:40 offset1:56
	ds_write2_b32 v82, v93, v97 offset0:172 offset1:188
	s_nop 5
	ds_write2_b32 v80, v98, v84 offset0:64 offset1:80
	ds_write2_b32 v80, v99, v85 offset0:196 offset1:212
	ds_write2_b32 v82, v100, v86 offset0:72 offset1:88
	ds_write2_b32 v82, v101, v87 offset0:204 offset1:220
	v_mfma_f32_16x16x32_bf16 v[88:91], v[74:77], v[38:41], 0
	v_add_u32_e32 v84, 0xf0, v83
	v_add_u32_e32 v85, 0xe0, v83
	s_waitcnt vmcnt(0)
	v_mul_f32_e32 v73, v33, v7
	v_mfma_f32_16x16x32_bf16 v[74:77], v[74:77], v[34:37], 0
	s_nop 7
	ds_write2_b32 v80, v88, v74 offset0:96 offset1:112
	ds_write2_b32 v80, v89, v75 offset0:228 offset1:244
	ds_write2_b32 v82, v90, v76 offset0:104 offset1:120
	ds_write2_b32 v82, v91, v77 offset0:236 offset1:252
	s_waitcnt lgkmcnt(0)
	ds_read2st64_b32 v[58:59], v84 offset0:42 offset1:43
	ds_read2st64_b32 v[74:75], v85 offset0:40 offset1:41
	v_fma_f32 v73, v32, v6, -v73
	v_mul_f32_e32 v6, v33, v6
	v_fmac_f32_e32 v6, v32, v7
	s_waitcnt lgkmcnt(1)
	v_add_f32_e32 v58, v73, v58
	v_add_f32_e32 v6, v6, v59
	v_add_u32_e32 v86, 0xd0, v83
	v_cvt_pk_bf16_f32 v7, v58, v6
	ds_read2st64_b32 v[76:77], v86 offset0:38 offset1:39
	s_waitcnt lgkmcnt(1)
	v_fma_f32 v59, -v6, v33, v74
	v_fma_f32 v6, v6, v32, v75
	v_fma_f32 v6, v58, v33, v6
	v_fma_f32 v59, v58, v32, v59
	v_add_u32_e32 v87, 0xc0, v83
	v_add_u32_e32 v88, 0xb0, v83
	v_add_u32_e32 v89, 0xa0, v83
	v_add_u32_e32 v90, 0x90, v83
	v_add_u32_e32 v91, 0x80, v83
	v_add_u32_e32 v92, 0x70, v83
	v_add_u32_e32 v93, 0x60, v83
	v_add_u32_e32 v94, 0x50, v83
	v_add_u32_e32 v95, 64, v83
	v_add_u32_e32 v96, 48, v83
	v_add_u32_e32 v97, 32, v83
	v_add_u32_e32 v98, 16, v83
	v_cvt_pk_bf16_f32 v58, v59, v6
	v_add_u32_e32 v99, 0x3a00, v83
	ds_read2st64_b32 v[100:101], v87 offset0:36 offset1:37
	ds_read2st64_b32 v[102:103], v88 offset0:34 offset1:35
	ds_read2st64_b32 v[104:105], v89 offset0:32 offset1:33
	ds_read2st64_b32 v[106:107], v90 offset0:30 offset1:31
	ds_read2st64_b32 v[108:109], v91 offset0:28 offset1:29
	ds_read2st64_b32 v[110:111], v92 offset0:26 offset1:27
	ds_read2st64_b32 v[112:113], v93 offset0:24 offset1:25
	ds_read2st64_b32 v[114:115], v94 offset0:22 offset1:23
	ds_read2st64_b32 v[116:117], v95 offset0:20 offset1:21
	ds_read2st64_b32 v[118:119], v96 offset0:18 offset1:19
	ds_read2st64_b32 v[120:121], v97 offset0:16 offset1:17
	ds_read2st64_b32 v[122:123], v98 offset0:14 offset1:15
	ds_read2st64_b32 v[124:125], v83 offset0:12 offset1:13
	ds_write2_b32 v99, v58, v7 offset0:120 offset1:188
	s_waitcnt lgkmcnt(14)
	v_fma_f32 v58, v33, v59, v77
	v_fma_f32 v7, v32, v59, v76
	v_fma_f32 v7, -v33, v6, v7
	v_fma_f32 v6, v32, v6, v58
	v_cvt_pk_bf16_f32 v58, v7, v6
	s_waitcnt lgkmcnt(13)
	v_fma_f32 v59, -v6, v33, v100
	v_fma_f32 v6, v6, v32, v101
	v_fma_f32 v6, v7, v33, v6
	v_fma_f32 v59, v7, v32, v59
	v_cvt_pk_bf16_f32 v7, v59, v6
	v_add_u32_e32 v100, 0x3800, v83
	ds_write2_b32 v100, v7, v58 offset0:112 offset1:180
	s_waitcnt lgkmcnt(13)
	v_fma_f32 v58, v33, v59, v103
	v_fma_f32 v7, v32, v59, v102
	v_fma_f32 v7, -v33, v6, v7
	v_fma_f32 v6, v32, v6, v58
	v_cvt_pk_bf16_f32 v58, v7, v6
	s_waitcnt lgkmcnt(12)
	v_fma_f32 v59, -v6, v33, v104
	v_fma_f32 v6, v6, v32, v105
	v_fma_f32 v6, v7, v33, v6
	v_fma_f32 v59, v7, v32, v59
	v_cvt_pk_bf16_f32 v7, v59, v6
	v_add_u32_e32 v101, 0x3600, v83
	ds_write2_b32 v101, v7, v58 offset0:104 offset1:172
	s_waitcnt lgkmcnt(12)
	v_fma_f32 v58, v33, v59, v107
	v_fma_f32 v7, v32, v59, v106
	v_fma_f32 v7, -v33, v6, v7
	v_fma_f32 v6, v32, v6, v58
	v_cvt_pk_bf16_f32 v58, v7, v6
	s_waitcnt lgkmcnt(11)
	v_fma_f32 v59, -v6, v33, v108
	v_fma_f32 v6, v6, v32, v109
	v_fma_f32 v6, v7, v33, v6
	v_fma_f32 v59, v7, v32, v59
	v_cvt_pk_bf16_f32 v7, v59, v6
	v_add_u32_e32 v102, 0x3400, v83
	ds_write2_b32 v102, v7, v58 offset0:96 offset1:164
	s_waitcnt lgkmcnt(11)
	v_fma_f32 v58, v33, v59, v111
	v_fma_f32 v7, v32, v59, v110
	v_fma_f32 v7, -v33, v6, v7
	v_fma_f32 v6, v32, v6, v58
	v_cvt_pk_bf16_f32 v58, v7, v6
	s_waitcnt lgkmcnt(10)
	v_fma_f32 v59, -v6, v33, v112
	v_fma_f32 v6, v6, v32, v113
	v_fma_f32 v6, v7, v33, v6
	v_fma_f32 v59, v7, v32, v59
	v_cvt_pk_bf16_f32 v7, v59, v6
	v_add_u32_e32 v103, 0x3200, v83
	ds_write2_b32 v103, v7, v58 offset0:88 offset1:156
	s_waitcnt lgkmcnt(10)
	v_fma_f32 v58, v33, v59, v115
	v_fma_f32 v7, v32, v59, v114
	v_fma_f32 v7, -v33, v6, v7
	v_fma_f32 v6, v32, v6, v58
	v_cvt_pk_bf16_f32 v58, v7, v6
	s_waitcnt lgkmcnt(9)
	v_fma_f32 v59, -v6, v33, v116
	v_fma_f32 v6, v6, v32, v117
	v_fma_f32 v6, v7, v33, v6
	v_fma_f32 v59, v7, v32, v59
	v_cvt_pk_bf16_f32 v7, v59, v6
	v_add_u32_e32 v104, 0x3000, v83
	ds_write2_b32 v104, v7, v58 offset0:80 offset1:148
	s_waitcnt lgkmcnt(9)
	v_fma_f32 v58, v33, v59, v119
	v_fma_f32 v7, v32, v59, v118
	v_fma_f32 v7, -v33, v6, v7
	v_fma_f32 v6, v32, v6, v58
	v_cvt_pk_bf16_f32 v58, v7, v6
	s_waitcnt lgkmcnt(8)
	v_fma_f32 v59, -v6, v33, v120
	v_fma_f32 v6, v6, v32, v121
	v_fma_f32 v6, v7, v33, v6
	v_fma_f32 v59, v7, v32, v59
	v_cvt_pk_bf16_f32 v7, v59, v6
	v_add_u32_e32 v105, 0x2e00, v83
	ds_write2_b32 v105, v7, v58 offset0:72 offset1:140
	s_waitcnt lgkmcnt(8)
	v_fma_f32 v58, v33, v59, v123
	v_fma_f32 v7, v32, v59, v122
	v_fma_f32 v7, -v33, v6, v7
	v_fma_f32 v58, v32, v6, v58
	v_mul_f32_e32 v6, v33, v58
	v_cvt_pk_bf16_f32 v59, v7, v58
	v_fma_f32 v6, v32, v7, -v6
	v_mul_f32_e32 v7, v33, v7
	v_fmac_f32_e32 v7, v32, v58
	s_waitcnt lgkmcnt(7)
	v_add_f32_e32 v6, v124, v6
	v_add_f32_e32 v7, v125, v7
	v_cvt_pk_bf16_f32 v58, v6, v7
	v_add_u32_e32 v106, 0x2c00, v83
	ds_write2_b32 v106, v58, v59 offset0:64 offset1:132
	s_waitcnt lgkmcnt(0)
	v_add_u32_e32 v79, v126, v0
	ds_read_b128 v[74:77], v79 offset:11520
	ds_read_b128 v[108:111], v79 offset:11584
	s_waitcnt lgkmcnt(1)
	v_mfma_f32_16x16x32_bf16 v[12:15], v[74:77], v[20:23], v[12:15]
	ds_read_b128 v[74:77], v79 offset:11648
	v_mov_b32_e32 v73, 0
	s_waitcnt lgkmcnt(1)
	v_mfma_f32_16x16x32_bf16 v[12:15], v[108:111], v[28:31], v[12:15]
	ds_read_b128 v[108:111], v79 offset:11712
	s_waitcnt lgkmcnt(1)
	v_mfma_f32_16x16x32_bf16 v[12:15], v[74:77], v[24:27], v[12:15]
	v_mov_b32_e32 v74, 0
	v_mov_b32_e32 v75, 0
	s_waitcnt lgkmcnt(0)
	v_mfma_f32_16x16x32_bf16 v[12:15], v[108:111], v[16:19], v[12:15]
	s_and_saveexec_b64 s[4:5], vcc
	ds_read_b128 v[72:75], v81 offset:1536
	s_or_b64 exec, exec, s[4:5]
	s_waitcnt lgkmcnt(0)
	v_mfma_f32_16x16x32_bf16 v[108:111], v[72:75], v[42:45], 0
	v_mul_f32_e32 v0, v33, v7
	v_fma_f32 v0, v32, v6, -v0
	v_mul_f32_e32 v6, v33, v6
	v_mfma_f32_16x16x32_bf16 v[112:115], v[72:75], v[68:71], 0
	s_nop 7
	ds_write2_b32 v80, v108, v112 offset1:16
	ds_write2_b32 v80, v109, v113 offset0:132 offset1:148
	ds_write2_b32 v82, v110, v114 offset0:8 offset1:24
	v_mfma_f32_16x16x32_bf16 v[116:119], v[72:75], v[64:67], 0
	v_fmac_f32_e32 v6, v32, v7
	v_mfma_f32_16x16x32_bf16 v[120:123], v[72:75], v[50:53], 0
	ds_write2_b32 v82, v111, v115 offset0:140 offset1:156
	s_nop 6
	ds_write2_b32 v80, v116, v120 offset0:32 offset1:48
	ds_write2_b32 v80, v117, v121 offset0:164 offset1:180
	v_mfma_f32_16x16x32_bf16 v[124:127], v[72:75], v[54:57], 0
	v_mfma_f32_16x16x32_bf16 v[108:111], v[72:75], v[46:49], 0
	ds_write2_b32 v82, v118, v122 offset0:40 offset1:56
	ds_write2_b32 v82, v119, v123 offset0:172 offset1:188
	s_nop 5
	ds_write2_b32 v80, v124, v108 offset0:64 offset1:80
	ds_write2_b32 v80, v125, v109 offset0:196 offset1:212
	ds_write2_b32 v82, v126, v110 offset0:72 offset1:88
	ds_write2_b32 v82, v127, v111 offset0:204 offset1:220
	v_mfma_f32_16x16x32_bf16 v[112:115], v[72:75], v[38:41], 0
	v_mfma_f32_16x16x32_bf16 v[72:75], v[72:75], v[34:37], 0
	s_nop 7
	ds_write2_b32 v80, v112, v72 offset0:96 offset1:112
	ds_write2_b32 v80, v113, v73 offset0:228 offset1:244
	ds_write2_b32 v82, v114, v74 offset0:104 offset1:120
	ds_write2_b32 v82, v115, v75 offset0:236 offset1:252
	s_waitcnt lgkmcnt(0)
	ds_read2st64_b32 v[58:59], v84 offset0:42 offset1:43
	ds_read2st64_b32 v[72:73], v85 offset0:40 offset1:41
	ds_read2st64_b32 v[74:75], v86 offset0:38 offset1:39
	ds_read2st64_b32 v[76:77], v87 offset0:36 offset1:37
	ds_read2st64_b32 v[108:109], v88 offset0:34 offset1:35
	ds_read2st64_b32 v[110:111], v89 offset0:32 offset1:33
	ds_read2st64_b32 v[112:113], v90 offset0:30 offset1:31
	ds_read2st64_b32 v[114:115], v91 offset0:28 offset1:29
	ds_read2st64_b32 v[116:117], v92 offset0:26 offset1:27
	ds_read2st64_b32 v[118:119], v93 offset0:24 offset1:25
	ds_read2st64_b32 v[120:121], v94 offset0:22 offset1:23
	ds_read2st64_b32 v[122:123], v95 offset0:20 offset1:21
	ds_read2st64_b32 v[124:125], v96 offset0:18 offset1:19
	ds_read2st64_b32 v[126:127], v97 offset0:16 offset1:17
	ds_read2st64_b32 v[128:129], v98 offset0:14 offset1:15
	ds_read2st64_b32 v[130:131], v83 offset0:12 offset1:13
	s_waitcnt lgkmcnt(14)
	v_add_f32_e32 v0, v0, v58
	v_add_f32_e32 v6, v6, v59
	v_cvt_pk_bf16_f32 v7, v0, v6
	v_mul_f32_e32 v58, v33, v6
	v_mul_f32_e32 v6, v32, v6
	v_fma_f32 v58, v32, v0, -v58
	v_fmac_f32_e32 v6, v33, v0
	v_add_f32_e32 v58, v72, v58
	v_add_f32_e32 v0, v73, v6
	v_cvt_pk_bf16_f32 v6, v58, v0
	ds_write2_b32 v99, v6, v7 offset0:120 offset1:188
	s_waitcnt lgkmcnt(14)
	v_fma_f32 v7, v33, v58, v75
	v_fma_f32 v6, v32, v58, v74
	v_fma_f32 v6, -v33, v0, v6
	v_fma_f32 v0, v32, v0, v7
	v_cvt_pk_bf16_f32 v7, v6, v0
	s_waitcnt lgkmcnt(13)
	v_fma_f32 v58, -v0, v33, v76
	v_fma_f32 v0, v0, v32, v77
	v_fma_f32 v0, v6, v33, v0
	v_fma_f32 v58, v6, v32, v58
	v_cvt_pk_bf16_f32 v6, v58, v0
	ds_write2_b32 v100, v6, v7 offset0:112 offset1:180
	s_waitcnt lgkmcnt(13)
	v_fma_f32 v7, v33, v58, v109
	v_fma_f32 v6, v32, v58, v108
	v_fma_f32 v6, -v33, v0, v6
	v_fma_f32 v0, v32, v0, v7
	v_cvt_pk_bf16_f32 v7, v6, v0
	s_waitcnt lgkmcnt(12)
	v_fma_f32 v58, -v0, v33, v110
	v_fma_f32 v0, v0, v32, v111
	v_fma_f32 v0, v6, v33, v0
	v_fma_f32 v58, v6, v32, v58
	v_cvt_pk_bf16_f32 v6, v58, v0
	ds_write2_b32 v101, v6, v7 offset0:104 offset1:172
	s_waitcnt lgkmcnt(12)
	v_fma_f32 v7, v33, v58, v113
	v_fma_f32 v6, v32, v58, v112
	v_fma_f32 v6, -v33, v0, v6
	v_fma_f32 v0, v32, v0, v7
	v_cvt_pk_bf16_f32 v7, v6, v0
	s_waitcnt lgkmcnt(11)
	v_fma_f32 v58, -v0, v33, v114
	v_fma_f32 v0, v0, v32, v115
	v_fma_f32 v0, v6, v33, v0
	v_fma_f32 v58, v6, v32, v58
	v_cvt_pk_bf16_f32 v6, v58, v0
	ds_write2_b32 v102, v6, v7 offset0:96 offset1:164
	s_waitcnt lgkmcnt(11)
	v_fma_f32 v7, v33, v58, v117
	v_fma_f32 v6, v32, v58, v116
	v_fma_f32 v6, -v33, v0, v6
	v_fma_f32 v0, v32, v0, v7
	v_cvt_pk_bf16_f32 v7, v6, v0
	s_waitcnt lgkmcnt(10)
	v_fma_f32 v58, -v0, v33, v118
	v_fma_f32 v0, v0, v32, v119
	v_fma_f32 v0, v6, v33, v0
	v_fma_f32 v58, v6, v32, v58
	v_cvt_pk_bf16_f32 v6, v58, v0
	ds_write2_b32 v103, v6, v7 offset0:88 offset1:156
	s_waitcnt lgkmcnt(10)
	v_fma_f32 v7, v33, v58, v121
	v_fma_f32 v6, v32, v58, v120
	v_fma_f32 v6, -v33, v0, v6
	v_fma_f32 v0, v32, v0, v7
	v_cvt_pk_bf16_f32 v7, v6, v0
	s_waitcnt lgkmcnt(9)
	v_fma_f32 v58, -v0, v33, v122
	v_fma_f32 v0, v0, v32, v123
	v_fma_f32 v0, v6, v33, v0
	v_fma_f32 v58, v6, v32, v58
	v_cvt_pk_bf16_f32 v6, v58, v0
	ds_write2_b32 v104, v6, v7 offset0:80 offset1:148
	s_waitcnt lgkmcnt(9)
	v_fma_f32 v7, v33, v58, v125
	v_fma_f32 v6, v32, v58, v124
	v_fma_f32 v6, -v33, v0, v6
	v_fma_f32 v0, v32, v0, v7
	v_cvt_pk_bf16_f32 v7, v6, v0
	s_waitcnt lgkmcnt(8)
	v_fma_f32 v58, -v0, v33, v126
	v_fma_f32 v0, v0, v32, v127
	v_fma_f32 v0, v6, v33, v0
	v_fma_f32 v58, v6, v32, v58
	v_cvt_pk_bf16_f32 v6, v58, v0
	ds_write2_b32 v105, v6, v7 offset0:72 offset1:140
	s_waitcnt lgkmcnt(8)
	v_fma_f32 v7, v33, v58, v129
	v_fma_f32 v6, v32, v58, v128
	v_fma_f32 v6, -v33, v0, v6
	v_fma_f32 v7, v32, v0, v7
	v_mul_f32_e32 v0, v33, v7
	v_cvt_pk_bf16_f32 v58, v6, v7
	v_fma_f32 v0, v32, v6, -v0
	v_mul_f32_e32 v6, v33, v6
	v_fmac_f32_e32 v6, v32, v7
	s_waitcnt lgkmcnt(7)
	v_add_f32_e32 v0, v130, v0
	v_add_f32_e32 v6, v131, v6
	v_cvt_pk_bf16_f32 v7, v0, v6
	ds_write2_b32 v106, v7, v58 offset0:64 offset1:132
	s_waitcnt lgkmcnt(0)
	ds_read_b128 v[72:75], v79 offset:11520
	ds_read_b128 v[108:111], v79 offset:11584
	s_waitcnt lgkmcnt(1)
	v_mfma_f32_16x16x32_bf16 v[58:61], v[72:75], v[20:23], v[60:63]
	ds_read_b128 v[72:75], v79 offset:11648
	v_mov_b32_e32 v76, 0
	v_mov_b32_e32 v77, 0
	s_waitcnt lgkmcnt(1)
	v_mfma_f32_16x16x32_bf16 v[58:61], v[108:111], v[28:31], v[58:61]
	ds_read_b128 v[108:111], v79 offset:11712
	s_waitcnt lgkmcnt(1)
	v_mfma_f32_16x16x32_bf16 v[58:61], v[72:75], v[24:27], v[58:61]
	v_mov_b32_e32 v72, 0
	v_mov_b32_e32 v74, 0
	v_mov_b32_e32 v75, 0
	s_waitcnt lgkmcnt(0)
	v_mfma_f32_16x16x32_bf16 v[58:61], v[108:111], v[16:19], v[58:61]
	s_and_saveexec_b64 s[4:5], vcc
	ds_read_b128 v[74:77], v81 offset:768
	s_or_b64 exec, exec, s[4:5]
	s_waitcnt lgkmcnt(0)
	v_mfma_f32_16x16x32_bf16 v[108:111], v[74:77], v[42:45], 0
	v_mul_f32_e32 v7, v33, v6
	v_fma_f32 v7, v32, v0, -v7
	v_mul_f32_e32 v0, v33, v0
	v_mfma_f32_16x16x32_bf16 v[112:115], v[74:77], v[68:71], 0
	s_nop 7
	ds_write2_b32 v80, v108, v112 offset1:16
	ds_write2_b32 v80, v109, v113 offset0:132 offset1:148
	ds_write2_b32 v82, v110, v114 offset0:8 offset1:24
	v_mfma_f32_16x16x32_bf16 v[116:119], v[74:77], v[64:67], 0
	v_fmac_f32_e32 v0, v32, v6
	v_mov_b32_e32 v73, 0
	v_mfma_f32_16x16x32_bf16 v[120:123], v[74:77], v[50:53], 0
	ds_write2_b32 v82, v111, v115 offset0:140 offset1:156
	s_nop 6
	ds_write2_b32 v80, v116, v120 offset0:32 offset1:48
	ds_write2_b32 v80, v117, v121 offset0:164 offset1:180
	v_mfma_f32_16x16x32_bf16 v[124:127], v[74:77], v[54:57], 0
	v_mfma_f32_16x16x32_bf16 v[108:111], v[74:77], v[46:49], 0
	ds_write2_b32 v82, v118, v122 offset0:40 offset1:56
	ds_write2_b32 v82, v119, v123 offset0:172 offset1:188
	s_nop 5
	ds_write2_b32 v80, v124, v108 offset0:64 offset1:80
	ds_write2_b32 v80, v125, v109 offset0:196 offset1:212
	ds_write2_b32 v82, v126, v110 offset0:72 offset1:88
	ds_write2_b32 v82, v127, v111 offset0:204 offset1:220
	v_mfma_f32_16x16x32_bf16 v[112:115], v[74:77], v[38:41], 0
	v_mfma_f32_16x16x32_bf16 v[74:77], v[74:77], v[34:37], 0
	s_nop 7
	ds_write2_b32 v80, v112, v74 offset0:96 offset1:112
	ds_write2_b32 v80, v113, v75 offset0:228 offset1:244
	ds_write2_b32 v82, v114, v76 offset0:104 offset1:120
	ds_write2_b32 v82, v115, v77 offset0:236 offset1:252
	s_waitcnt lgkmcnt(0)
	ds_read2st64_b32 v[62:63], v84 offset0:42 offset1:43
	ds_read2st64_b32 v[74:75], v85 offset0:40 offset1:41
	ds_read2st64_b32 v[76:77], v86 offset0:38 offset1:39
	ds_read2st64_b32 v[108:109], v87 offset0:36 offset1:37
	ds_read2st64_b32 v[110:111], v88 offset0:34 offset1:35
	ds_read2st64_b32 v[112:113], v89 offset0:32 offset1:33
	ds_read2st64_b32 v[114:115], v90 offset0:30 offset1:31
	ds_read2st64_b32 v[116:117], v91 offset0:28 offset1:29
	ds_read2st64_b32 v[118:119], v92 offset0:26 offset1:27
	ds_read2st64_b32 v[120:121], v93 offset0:24 offset1:25
	ds_read2st64_b32 v[122:123], v94 offset0:22 offset1:23
	ds_read2st64_b32 v[124:125], v95 offset0:20 offset1:21
	ds_read2st64_b32 v[126:127], v96 offset0:18 offset1:19
	ds_read2st64_b32 v[128:129], v97 offset0:16 offset1:17
	ds_read2st64_b32 v[130:131], v98 offset0:14 offset1:15
	ds_read2st64_b32 v[132:133], v83 offset0:12 offset1:13
	s_waitcnt lgkmcnt(14)
	v_add_f32_e32 v7, v7, v62
	v_add_f32_e32 v0, v0, v63
	v_cvt_pk_bf16_f32 v6, v7, v0
	v_fma_f32 v62, -v0, v33, v74
	v_fma_f32 v0, v0, v32, v75
	v_fma_f32 v0, v7, v33, v0
	v_fma_f32 v62, v7, v32, v62
	v_cvt_pk_bf16_f32 v7, v62, v0
	ds_write2_b32 v99, v7, v6 offset0:120 offset1:188
	s_waitcnt lgkmcnt(14)
	v_fma_f32 v7, v33, v62, v77
	v_fma_f32 v6, v32, v62, v76
	v_fma_f32 v6, -v33, v0, v6
	v_fma_f32 v0, v32, v0, v7
	v_cvt_pk_bf16_f32 v7, v6, v0
	s_waitcnt lgkmcnt(13)
	v_fma_f32 v62, -v0, v33, v108
	v_fma_f32 v0, v0, v32, v109
	v_fma_f32 v0, v6, v33, v0
	v_fma_f32 v62, v6, v32, v62
	v_cvt_pk_bf16_f32 v6, v62, v0
	ds_write2_b32 v100, v6, v7 offset0:112 offset1:180
	s_waitcnt lgkmcnt(13)
	v_fma_f32 v7, v33, v62, v111
	v_fma_f32 v6, v32, v62, v110
	v_fma_f32 v6, -v33, v0, v6
	v_fma_f32 v0, v32, v0, v7
	v_cvt_pk_bf16_f32 v7, v6, v0
	s_waitcnt lgkmcnt(12)
	v_fma_f32 v62, -v0, v33, v112
	v_fma_f32 v0, v0, v32, v113
	v_fma_f32 v0, v6, v33, v0
	v_fma_f32 v62, v6, v32, v62
	v_cvt_pk_bf16_f32 v6, v62, v0
	ds_write2_b32 v101, v6, v7 offset0:104 offset1:172
	s_waitcnt lgkmcnt(12)
	v_fma_f32 v7, v33, v62, v115
	v_fma_f32 v6, v32, v62, v114
	v_fma_f32 v6, -v33, v0, v6
	v_fma_f32 v0, v32, v0, v7
	v_cvt_pk_bf16_f32 v7, v6, v0
	s_waitcnt lgkmcnt(11)
	v_fma_f32 v62, -v0, v33, v116
	v_fma_f32 v0, v0, v32, v117
	v_fma_f32 v0, v6, v33, v0
	v_fma_f32 v62, v6, v32, v62
	v_cvt_pk_bf16_f32 v6, v62, v0
	ds_write2_b32 v102, v6, v7 offset0:96 offset1:164
	s_waitcnt lgkmcnt(11)
	v_fma_f32 v7, v33, v62, v119
	v_fma_f32 v6, v32, v62, v118
	v_fma_f32 v6, -v33, v0, v6
	v_fma_f32 v0, v32, v0, v7
	v_cvt_pk_bf16_f32 v7, v6, v0
	s_waitcnt lgkmcnt(10)
	v_fma_f32 v62, -v0, v33, v120
	v_fma_f32 v0, v0, v32, v121
	v_fma_f32 v0, v6, v33, v0
	v_fma_f32 v62, v6, v32, v62
	v_cvt_pk_bf16_f32 v6, v62, v0
	ds_write2_b32 v103, v6, v7 offset0:88 offset1:156
	s_waitcnt lgkmcnt(10)
	v_fma_f32 v7, v33, v62, v123
	v_fma_f32 v6, v32, v62, v122
	v_fma_f32 v6, -v33, v0, v6
	v_fma_f32 v0, v32, v0, v7
	v_cvt_pk_bf16_f32 v7, v6, v0
	s_waitcnt lgkmcnt(9)
	v_fma_f32 v62, -v0, v33, v124
	v_fma_f32 v0, v0, v32, v125
	v_fma_f32 v0, v6, v33, v0
	v_fma_f32 v62, v6, v32, v62
	v_cvt_pk_bf16_f32 v6, v62, v0
	ds_write2_b32 v104, v6, v7 offset0:80 offset1:148
	s_waitcnt lgkmcnt(9)
	v_fma_f32 v7, v33, v62, v127
	v_fma_f32 v6, v32, v62, v126
	v_fma_f32 v6, -v33, v0, v6
	v_fma_f32 v0, v32, v0, v7
	v_cvt_pk_bf16_f32 v7, v6, v0
	s_waitcnt lgkmcnt(8)
	v_fma_f32 v62, -v0, v33, v128
	v_fma_f32 v0, v0, v32, v129
	v_fma_f32 v0, v6, v33, v0
	v_fma_f32 v62, v6, v32, v62
	v_cvt_pk_bf16_f32 v6, v62, v0
	ds_write2_b32 v105, v6, v7 offset0:72 offset1:140
	s_waitcnt lgkmcnt(8)
	v_fma_f32 v7, v33, v62, v131
	v_fma_f32 v6, v32, v62, v130
	v_fma_f32 v6, -v33, v0, v6
	v_fma_f32 v7, v32, v0, v7
	v_cvt_pk_bf16_f32 v63, v6, v7
	s_waitcnt lgkmcnt(7)
	v_fma_f32 v0, -v33, v7, v132
	v_fma_f32 v62, v33, v6, v133
	v_fma_f32 v62, v32, v7, v62
	v_fma_f32 v0, v32, v6, v0
	v_cvt_pk_bf16_f32 v6, v0, v62
	ds_write2_b32 v106, v6, v63 offset0:64 offset1:132
	s_waitcnt lgkmcnt(0)
	ds_read_b128 v[74:77], v79 offset:11520
	ds_read_b128 v[108:111], v79 offset:11584
	s_waitcnt lgkmcnt(1)
	v_mfma_f32_16x16x32_bf16 v[6:9], v[74:77], v[20:23], v[8:11]
	ds_read_b128 v[74:77], v79 offset:11648
	s_waitcnt lgkmcnt(1)
	v_mfma_f32_16x16x32_bf16 v[6:9], v[108:111], v[28:31], v[6:9]
	ds_read_b128 v[108:111], v79 offset:11712
	s_waitcnt lgkmcnt(1)
	v_mfma_f32_16x16x32_bf16 v[6:9], v[74:77], v[24:27], v[6:9]
	v_mov_b32_e32 v74, 0
	v_mov_b32_e32 v75, 0
	s_waitcnt lgkmcnt(0)
	v_mfma_f32_16x16x32_bf16 v[6:9], v[108:111], v[16:19], v[6:9]
	s_and_saveexec_b64 s[4:5], vcc
	s_cbranch_execz .LBB0_275
	ds_read_b128 v[72:75], v81
	s_branch .LBB0_275
